# baseline (speedup 1.0000x reference)
; #define STAGE(P, q) do { GLDS16(q[0], (unsigned char*)(P) + wid * 1024); GLDS16(q[1], (unsigned char*)(P) + wid * 1024 + 8192); \
;     q[0] += 128; q[1] += 128; asm volatile("" : "+v"(q[0]), "+v"(q[1])); } while (0)
; #define LDA(dst, b, h) _Pragma("unroll") for (int m = 0; m < 4; ++m) _Pragma("unroll") for (int k = 0; k < 2; ++k) \
;     dst[m][k] = *(const bf16x8*)((const unsigned char*)SA(b, h) + lds_byte1(wr * 64 + m * 16 + fr, k * 32 + fq * 8))
; #define LDB(dst, b, h) _Pragma("unroll") for (int n = 0; n < 2; ++n) _Pragma("unroll") for (int k = 0; k < 2; ++k) \
;     dst[n][k] = *(const bf16x8*)((const unsigned char*)SB(b, h) + lds_byte1(wc * 32 + n * 16 + fr, k * 32 + fq * 8))
; #define MMA(ai, bj, At_, Bt_) do { __builtin_amdgcn_s_setprio(1); \
;     _Pragma("unroll") for (int m = 0; m < 4; ++m) _Pragma("unroll") for (int n = 0; n < 2; ++n) _Pragma("unroll") for (int k = 0; k < 2; ++k) \
;       acc[ai][bj][m][n] = mfma16(At_[m][k], Bt_[n][k], acc[ai][bj][m][n]); \
;     __builtin_amdgcn_s_setprio(0); } while (0)
; #define WAIT_V(n) asm volatile("s_waitcnt vmcnt(" #n ")" ::: "memory")
; #define WAIT_L(n) asm volatile("s_waitcnt lgkmcnt(" #n ")" ::: "memory")
; #define BAR __builtin_amdgcn_s_barrier()
; #define SCHED __builtin_amdgcn_sched_barrier(0)
; DEV void gemm_tile(const u16* __restrict__ A, const u16* __restrict__ Bt, u16* __restrict__ C, int N, int K,
;                    int brow, int bcol, unsigned char* smem, int epi, const GateEpi& ge) {
;     ...
;   for (int t = 0; t < nt - 2; t += 2) {
;     LDB(B0, 0, 0); SCHED; LDA(At, 0, 0); STAGE(SA(1, 1), qA1);
;     WAIT_L(8); BAR; WAIT_L(0); MMA(0, 0, At, B0); BAR; SCHED;
;     LDB(B1, 0, 1); STAGE(SB(0, 0), qB0);
;     BAR; WAIT_L(0); MMA(0, 1, At, B1); BAR;
;     LDA(At, 0, 1); STAGE(SA(0, 0), qA0);
;     BAR; WAIT_L(0); MMA(1, 0, At, B0); BAR; SCHED;
;     STAGE(SB(0, 1), qB1);
;     WAIT_V(6); BAR; MMA(1, 1, At, B1); BAR;
.LBB0_634:
	ds_read_b128 v[156:159], v152
	ds_read_b128 v[180:183], v152 offset:1024
	ds_read_b128 v[184:187], v152 offset:256
	ds_read_b128 v[188:191], v152 offset:1280
	s_mov_b32 m0, s56
	v_add_u32_e32 v153, s53, v151
	v_add_u32_e32 v154, s54, v151
	v_add_u32_e32 v155, s55, v151
	ds_read_b128 v[192:195], v128
	ds_read_b128 v[196:199], v128 offset:1024
	ds_read_b128 v[200:203], v153
	ds_read_b128 v[204:207], v153 offset:1024
	ds_read_b128 v[208:211], v154
	ds_read_b128 v[212:215], v154 offset:1024
	ds_read_b128 v[216:219], v155
	ds_read_b128 v[220:223], v155 offset:1024
	global_load_lds_dwordx4 v[132:133], off
	s_mov_b32 m0, s52
	v_lshl_add_u64 v[236:237], v[132:133], 0, s[8:9]
	global_load_lds_dwordx4 v[134:135], off
	v_lshl_add_u64 v[238:239], v[134:135], 0, s[8:9]
	s_waitcnt lgkmcnt(8)
	s_barrier
	s_waitcnt lgkmcnt(0)
	s_setprio 1
	s_waitcnt lgkmcnt(0)
	v_mfma_f32_16x16x32_bf16 v[124:127], v[156:159], v[192:195], v[124:127]
	v_mfma_f32_16x16x32_bf16 v[120:123], v[184:187], v[192:195], v[120:123]
	v_mfma_f32_16x16x32_bf16 v[116:119], v[156:159], v[200:203], v[116:119]
	v_mfma_f32_16x16x32_bf16 v[112:115], v[184:187], v[200:203], v[112:115]
	v_mfma_f32_16x16x32_bf16 v[108:111], v[156:159], v[208:211], v[108:111]
	v_mfma_f32_16x16x32_bf16 v[104:107], v[184:187], v[208:211], v[104:107]
	v_mfma_f32_16x16x32_bf16 v[100:103], v[156:159], v[216:219], v[100:103]
	v_mfma_f32_16x16x32_bf16 v[96:99], v[184:187], v[216:219], v[96:99]
	v_mfma_f32_16x16x32_bf16 v[124:127], v[180:183], v[196:199], v[124:127]
	v_mfma_f32_16x16x32_bf16 v[120:123], v[188:191], v[196:199], v[120:123]
	v_mfma_f32_16x16x32_bf16 v[116:119], v[180:183], v[204:207], v[116:119]
	v_mfma_f32_16x16x32_bf16 v[112:115], v[188:191], v[204:207], v[112:115]
	s_barrier
	v_mfma_f32_16x16x32_bf16 v[108:111], v[180:183], v[212:215], v[108:111]
	v_mfma_f32_16x16x32_bf16 v[104:107], v[188:191], v[212:215], v[104:107]
	v_mfma_f32_16x16x32_bf16 v[100:103], v[180:183], v[220:223], v[100:103]
	v_mfma_f32_16x16x32_bf16 v[96:99], v[188:191], v[220:223], v[96:99]
	s_setprio 0
	s_mov_b32 m0, s4
	ds_read_b128 v[132:135], v150
	ds_read_b128 v[224:227], v150 offset:1024
	ds_read_b128 v[228:231], v150 offset:256
	ds_read_b128 v[232:235], v150 offset:1280
	global_load_lds_dwordx4 v[136:137], off
	s_mov_b32 m0, s5
	v_lshl_add_u64 v[240:241], v[136:137], 0, s[8:9]
	global_load_lds_dwordx4 v[138:139], off
	v_lshl_add_u64 v[242:243], v[138:139], 0, s[8:9]
	s_barrier
	s_waitcnt lgkmcnt(0)
	s_setprio 1
	s_waitcnt lgkmcnt(0)
	v_mfma_f32_16x16x32_bf16 v[84:87], v[132:135], v[192:195], v[84:87]
	v_mfma_f32_16x16x32_bf16 v[68:71], v[228:231], v[192:195], v[68:71]
	v_mfma_f32_16x16x32_bf16 v[52:55], v[132:135], v[200:203], v[52:55]
	v_mfma_f32_16x16x32_bf16 v[48:51], v[228:231], v[200:203], v[48:51]
	v_mfma_f32_16x16x32_bf16 v[44:47], v[132:135], v[208:211], v[44:47]
	v_mfma_f32_16x16x32_bf16 v[40:43], v[228:231], v[208:211], v[40:43]
	v_mfma_f32_16x16x32_bf16 v[36:39], v[132:135], v[216:219], v[36:39]
	v_mfma_f32_16x16x32_bf16 v[32:35], v[228:231], v[216:219], v[32:35]
	v_mfma_f32_16x16x32_bf16 v[84:87], v[224:227], v[196:199], v[84:87]
	v_mfma_f32_16x16x32_bf16 v[68:71], v[232:235], v[196:199], v[68:71]
	v_mfma_f32_16x16x32_bf16 v[52:55], v[224:227], v[204:207], v[52:55]
	v_mfma_f32_16x16x32_bf16 v[48:51], v[232:235], v[204:207], v[48:51]
	s_barrier
	v_mfma_f32_16x16x32_bf16 v[44:47], v[224:227], v[212:215], v[44:47]
	v_mfma_f32_16x16x32_bf16 v[40:43], v[232:235], v[212:215], v[40:43]
	v_mfma_f32_16x16x32_bf16 v[36:39], v[224:227], v[220:223], v[36:39]
	v_mfma_f32_16x16x32_bf16 v[32:35], v[232:235], v[220:223], v[32:35]
	s_setprio 0
	s_mov_b32 m0, s1
	ds_read_b128 v[136:139], v128 offset:16384
	ds_read_b128 v[192:195], v128 offset:17408
	ds_read_b128 v[196:199], v153 offset:16384
	ds_read_b128 v[200:203], v153 offset:17408
	ds_read_b128 v[204:207], v154 offset:16384
	ds_read_b128 v[208:211], v154 offset:17408
	ds_read_b128 v[212:215], v155 offset:16384
	ds_read_b128 v[216:219], v155 offset:17408
	global_load_lds_dwordx4 v[140:141], off
	s_mov_b32 m0, s6
	v_lshl_add_u64 v[244:245], v[140:141], 0, s[8:9]
	global_load_lds_dwordx4 v[142:143], off
	v_lshl_add_u64 v[246:247], v[142:143], 0, s[8:9]
	s_barrier
	s_waitcnt lgkmcnt(0)
	s_setprio 1
	s_waitcnt lgkmcnt(0)
	v_mfma_f32_16x16x32_bf16 v[28:31], v[156:159], v[136:139], v[28:31]
	v_mfma_f32_16x16x32_bf16 v[24:27], v[184:187], v[136:139], v[24:27]
	v_mfma_f32_16x16x32_bf16 v[20:23], v[156:159], v[196:199], v[20:23]
	v_mfma_f32_16x16x32_bf16 v[16:19], v[184:187], v[196:199], v[16:19]
	v_mfma_f32_16x16x32_bf16 v[12:15], v[156:159], v[204:207], v[12:15]
	v_mfma_f32_16x16x32_bf16 v[8:11], v[184:187], v[204:207], v[8:11]
	v_mfma_f32_16x16x32_bf16 v[4:7], v[156:159], v[212:215], v[4:7]
	v_mfma_f32_16x16x32_bf16 v[0:3], v[184:187], v[212:215], v[0:3]
	v_mfma_f32_16x16x32_bf16 v[28:31], v[180:183], v[192:195], v[28:31]
	v_mfma_f32_16x16x32_bf16 v[24:27], v[188:191], v[192:195], v[24:27]
	v_mfma_f32_16x16x32_bf16 v[20:23], v[180:183], v[200:203], v[20:23]
	v_mfma_f32_16x16x32_bf16 v[16:19], v[188:191], v[200:203], v[16:19]
	s_barrier
	v_mfma_f32_16x16x32_bf16 v[12:15], v[180:183], v[208:211], v[12:15]
	v_mfma_f32_16x16x32_bf16 v[8:11], v[188:191], v[208:211], v[8:11]
	v_mfma_f32_16x16x32_bf16 v[4:7], v[180:183], v[216:219], v[4:7]
	v_mfma_f32_16x16x32_bf16 v[0:3], v[188:191], v[216:219], v[0:3]
	s_setprio 0
	s_mov_b32 m0, s7
	v_lshl_add_u64 v[248:249], v[144:145], 0, s[8:9]
	global_load_lds_dwordx4 v[144:145], off
	s_mov_b32 m0, s35
	v_lshl_add_u64 v[250:251], v[146:147], 0, s[8:9]
	global_load_lds_dwordx4 v[146:147], off
	s_waitcnt vmcnt(6)
	s_barrier
; #define STAGE(P, q) do { GLDS16(q[0], (unsigned char*)(P) + wid * 1024); GLDS16(q[1], (unsigned char*)(P) + wid * 1024 + 8192); \
;     q[0] += 128; q[1] += 128; asm volatile("" : "+v"(q[0]), "+v"(q[1])); } while (0)
; #define LDA(dst, b, h) _Pragma("unroll") for (int m = 0; m < 4; ++m) _Pragma("unroll") for (int k = 0; k < 2; ++k) \
;     dst[m][k] = *(const bf16x8*)((const unsigned char*)SA(b, h) + lds_byte1(wr * 64 + m * 16 + fr, k * 32 + fq * 8))
; #define LDB(dst, b, h) _Pragma("unroll") for (int n = 0; n < 2; ++n) _Pragma("unroll") for (int k = 0; k < 2; ++k) \
;     dst[n][k] = *(const bf16x8*)((const unsigned char*)SB(b, h) + lds_byte1(wc * 32 + n * 16 + fr, k * 32 + fq * 8))
; #define MMA(ai, bj, At_, Bt_) do { __builtin_amdgcn_s_setprio(1); \
;     _Pragma("unroll") for (int m = 0; m < 4; ++m) _Pragma("unroll") for (int n = 0; n < 2; ++n) _Pragma("unroll") for (int k = 0; k < 2; ++k) \
;       acc[ai][bj][m][n] = mfma16(At_[m][k], Bt_[n][k], acc[ai][bj][m][n]); \
;     __builtin_amdgcn_s_setprio(0); } while (0)
; #define WAIT_V(n) asm volatile("s_waitcnt vmcnt(" #n ")" ::: "memory")
; #define WAIT_L(n) asm volatile("s_waitcnt lgkmcnt(" #n ")" ::: "memory")
; #define BAR __builtin_amdgcn_s_barrier()
; #define SCHED __builtin_amdgcn_sched_barrier(0)
; DEV void gemm_tile(const u16* __restrict__ A, const u16* __restrict__ Bt, u16* __restrict__ C, int N, int K,
;                    int brow, int bcol, unsigned char* smem, int epi, const GateEpi& ge) {
;     ...
;     WAIT_V(6); BAR; MMA(1, 1, At, B1); BAR;
;     LDB(B0, 1, 0); SCHED; LDA(At, 1, 0); STAGE(SA(0, 1), qA1);
;     WAIT_L(8); BAR; WAIT_L(0); MMA(0, 0, At, B0); BAR; SCHED;
;     LDB(B1, 1, 1); STAGE(SB(1, 0), qB0);
;     BAR; WAIT_L(0); MMA(0, 1, At, B1); BAR;
;     LDA(At, 1, 1); STAGE(SA(1, 0), qA0);
;     BAR; WAIT_L(0); MMA(1, 0, At, B0); BAR; SCHED;
;     STAGE(SB(1, 1), qB1);
;     WAIT_V(6); BAR; MMA(1, 1, At, B1); BAR;
	s_setprio 1
	v_mfma_f32_16x16x32_bf16 v[56:59], v[132:135], v[136:139], v[56:59]
	v_mfma_f32_16x16x32_bf16 v[60:63], v[228:231], v[136:139], v[60:63]
	v_mfma_f32_16x16x32_bf16 v[64:67], v[132:135], v[196:199], v[64:67]
	v_mfma_f32_16x16x32_bf16 v[72:75], v[228:231], v[196:199], v[72:75]
	v_mfma_f32_16x16x32_bf16 v[76:79], v[132:135], v[204:207], v[76:79]
	v_mfma_f32_16x16x32_bf16 v[80:83], v[228:231], v[204:207], v[80:83]
	v_mfma_f32_16x16x32_bf16 v[88:91], v[132:135], v[212:215], v[88:91]
	v_mfma_f32_16x16x32_bf16 v[92:95], v[228:231], v[212:215], v[92:95]
	v_mfma_f32_16x16x32_bf16 v[56:59], v[224:227], v[192:195], v[56:59]
	v_mfma_f32_16x16x32_bf16 v[60:63], v[232:235], v[192:195], v[60:63]
	v_mfma_f32_16x16x32_bf16 v[64:67], v[224:227], v[200:203], v[64:67]
	v_mfma_f32_16x16x32_bf16 v[72:75], v[232:235], v[200:203], v[72:75]
	s_barrier
	v_mfma_f32_16x16x32_bf16 v[76:79], v[224:227], v[208:211], v[76:79]
	v_mfma_f32_16x16x32_bf16 v[80:83], v[232:235], v[208:211], v[80:83]
	v_mfma_f32_16x16x32_bf16 v[88:91], v[224:227], v[216:219], v[88:91]
	v_mfma_f32_16x16x32_bf16 v[92:95], v[232:235], v[216:219], v[92:95]
	s_setprio 0
	ds_read_b128 v[144:147], v149
	ds_read_b128 v[156:159], v149 offset:1024
	ds_read_b128 v[180:183], v149 offset:256
	ds_read_b128 v[184:187], v149 offset:1280
	s_mov_b32 m0, s41
	ds_read_b128 v[140:143], v128 offset:32768
	ds_read_b128 v[188:191], v128 offset:33792
	ds_read_b128 v[192:195], v153 offset:32768
	ds_read_b128 v[196:199], v153 offset:33792
	ds_read_b128 v[200:203], v154 offset:32768
	ds_read_b128 v[204:207], v154 offset:33792
	ds_read_b128 v[208:211], v155 offset:32768
	ds_read_b128 v[212:215], v155 offset:33792
	global_load_lds_dwordx4 v[236:237], off
	s_mov_b32 m0, vcc_lo
	v_lshl_add_u64 v[132:133], v[236:237], 0, s[8:9]
	global_load_lds_dwordx4 v[238:239], off
	v_lshl_add_u64 v[134:135], v[238:239], 0, s[8:9]
	s_waitcnt lgkmcnt(8)
	s_barrier
	s_waitcnt lgkmcnt(0)
	s_setprio 1
	s_waitcnt lgkmcnt(0)
	v_mfma_f32_16x16x32_bf16 v[124:127], v[144:147], v[140:143], v[124:127]
	v_mfma_f32_16x16x32_bf16 v[120:123], v[180:183], v[140:143], v[120:123]
	v_mfma_f32_16x16x32_bf16 v[116:119], v[144:147], v[192:195], v[116:119]
	v_mfma_f32_16x16x32_bf16 v[112:115], v[180:183], v[192:195], v[112:115]
	v_mfma_f32_16x16x32_bf16 v[108:111], v[144:147], v[200:203], v[108:111]
	v_mfma_f32_16x16x32_bf16 v[104:107], v[180:183], v[200:203], v[104:107]
	v_mfma_f32_16x16x32_bf16 v[100:103], v[144:147], v[208:211], v[100:103]
	v_mfma_f32_16x16x32_bf16 v[96:99], v[180:183], v[208:211], v[96:99]
	v_mfma_f32_16x16x32_bf16 v[124:127], v[156:159], v[188:191], v[124:127]
	v_mfma_f32_16x16x32_bf16 v[120:123], v[184:187], v[188:191], v[120:123]
	v_mfma_f32_16x16x32_bf16 v[116:119], v[156:159], v[196:199], v[116:119]
	v_mfma_f32_16x16x32_bf16 v[112:115], v[184:187], v[196:199], v[112:115]
	s_barrier
	v_mfma_f32_16x16x32_bf16 v[108:111], v[156:159], v[204:207], v[108:111]
	v_mfma_f32_16x16x32_bf16 v[104:107], v[184:187], v[204:207], v[104:107]
	v_mfma_f32_16x16x32_bf16 v[100:103], v[156:159], v[212:215], v[100:103]
	v_mfma_f32_16x16x32_bf16 v[96:99], v[184:187], v[212:215], v[96:99]
	s_setprio 0
	s_mov_b32 m0, vcc_hi
	ds_read_b128 v[216:219], v148
	ds_read_b128 v[220:223], v148 offset:1024
	ds_read_b128 v[224:227], v148 offset:256
	ds_read_b128 v[228:231], v148 offset:1280
	global_load_lds_dwordx4 v[240:241], off
	s_mov_b32 m0, s28
	v_lshl_add_u64 v[136:137], v[240:241], 0, s[8:9]
	global_load_lds_dwordx4 v[242:243], off
	v_lshl_add_u64 v[138:139], v[242:243], 0, s[8:9]
	s_barrier
	s_waitcnt lgkmcnt(0)
	s_setprio 1
	s_waitcnt lgkmcnt(0)
	v_mfma_f32_16x16x32_bf16 v[84:87], v[216:219], v[140:143], v[84:87]
	v_mfma_f32_16x16x32_bf16 v[68:71], v[224:227], v[140:143], v[68:71]
	v_mfma_f32_16x16x32_bf16 v[52:55], v[216:219], v[192:195], v[52:55]
	v_mfma_f32_16x16x32_bf16 v[48:51], v[224:227], v[192:195], v[48:51]
	v_mfma_f32_16x16x32_bf16 v[44:47], v[216:219], v[200:203], v[44:47]
	v_mfma_f32_16x16x32_bf16 v[40:43], v[224:227], v[200:203], v[40:43]
	v_mfma_f32_16x16x32_bf16 v[36:39], v[216:219], v[208:211], v[36:39]
	v_mfma_f32_16x16x32_bf16 v[32:35], v[224:227], v[208:211], v[32:35]
	v_mfma_f32_16x16x32_bf16 v[84:87], v[220:223], v[188:191], v[84:87]
	v_mfma_f32_16x16x32_bf16 v[68:71], v[228:231], v[188:191], v[68:71]
	v_mfma_f32_16x16x32_bf16 v[52:55], v[220:223], v[196:199], v[52:55]
	v_mfma_f32_16x16x32_bf16 v[48:51], v[228:231], v[196:199], v[48:51]
	s_barrier
	v_mfma_f32_16x16x32_bf16 v[44:47], v[220:223], v[204:207], v[44:47]
	v_mfma_f32_16x16x32_bf16 v[40:43], v[228:231], v[204:207], v[40:43]
	v_mfma_f32_16x16x32_bf16 v[36:39], v[220:223], v[212:215], v[36:39]
	v_mfma_f32_16x16x32_bf16 v[32:35], v[228:231], v[212:215], v[32:35]
	s_setprio 0
	s_mov_b32 m0, s94
	ds_read_b128 v[188:191], v128 offset:49152
	ds_read_b128 v[192:195], v128 offset:50176
	ds_read_b128 v[196:199], v153 offset:49152
	ds_read_b128 v[200:203], v153 offset:50176
	ds_read_b128 v[204:207], v154 offset:49152
	ds_read_b128 v[208:211], v154 offset:50176
	ds_read_b128 v[212:215], v155 offset:49152
	ds_read_b128 v[232:235], v155 offset:50176
	global_load_lds_dwordx4 v[244:245], off
	s_mov_b32 m0, s95
	v_lshl_add_u64 v[140:141], v[244:245], 0, s[8:9]
	global_load_lds_dwordx4 v[246:247], off
	v_lshl_add_u64 v[142:143], v[246:247], 0, s[8:9]
	s_barrier
; #define STAGE(P, q) do { GLDS16(q[0], (unsigned char*)(P) + wid * 1024); GLDS16(q[1], (unsigned char*)(P) + wid * 1024 + 8192); \
;     q[0] += 128; q[1] += 128; asm volatile("" : "+v"(q[0]), "+v"(q[1])); } while (0)
; #define LDA(dst, b, h) _Pragma("unroll") for (int m = 0; m < 4; ++m) _Pragma("unroll") for (int k = 0; k < 2; ++k) \
;     dst[m][k] = *(const bf16x8*)((const unsigned char*)SA(b, h) + lds_byte1(wr * 64 + m * 16 + fr, k * 32 + fq * 8))
; #define LDB(dst, b, h) _Pragma("unroll") for (int n = 0; n < 2; ++n) _Pragma("unroll") for (int k = 0; k < 2; ++k) \
;     dst[n][k] = *(const bf16x8*)((const unsigned char*)SB(b, h) + lds_byte1(wc * 32 + n * 16 + fr, k * 32 + fq * 8))
; #define MMA(ai, bj, At_, Bt_) do { __builtin_amdgcn_s_setprio(1); \
;     _Pragma("unroll") for (int m = 0; m < 4; ++m) _Pragma("unroll") for (int n = 0; n < 2; ++n) _Pragma("unroll") for (int k = 0; k < 2; ++k) \
;       acc[ai][bj][m][n] = mfma16(At_[m][k], Bt_[n][k], acc[ai][bj][m][n]); \
;     __builtin_amdgcn_s_setprio(0); } while (0)
; #define WAIT_V(n) asm volatile("s_waitcnt vmcnt(" #n ")" ::: "memory")
; #define WAIT_L(n) asm volatile("s_waitcnt lgkmcnt(" #n ")" ::: "memory")
; #define BAR __builtin_amdgcn_s_barrier()
; #define SCHED __builtin_amdgcn_sched_barrier(0)
; DEV void gemm_tile(const u16* __restrict__ A, const u16* __restrict__ Bt, u16* __restrict__ C, int N, int K,
;                    int brow, int bcol, unsigned char* smem, int epi, const GateEpi& ge) {
;     ...
;     BAR; WAIT_L(0); MMA(1, 0, At, B0); BAR; SCHED;
;     STAGE(SB(1, 1), qB1);
;     WAIT_V(6); BAR; MMA(1, 1, At, B1); BAR;
;   }
;   { LDB(B0, 0, 0); LDA(At, 0, 0); STAGE(SA(1, 1), qA1);
;     BAR; WAIT_L(0); MMA(0, 0, At, B0); BAR;
;     LDB(B1, 0, 1); BAR; WAIT_L(0); MMA(0, 1, At, B1); BAR;
;     LDA(At, 0, 1); WAIT_V(4); BAR; WAIT_L(0); MMA(1, 0, At, B0); MMA(1, 1, At, B1); BAR; }
;     ...
;     for (int n = 0; n < 2; ++n) {
;       const int cg = pn * 128 + wc * 32 + n * 16 + fr2;
;       w0[n] = ge.cw[cg]; w1[n] = ge.cw[DFF + cg]; w2[n] = ge.cw[2 * DFF + cg]; bs[n] = ge.cb[cg];
;     }
	s_waitcnt lgkmcnt(0)
	s_setprio 1
	s_waitcnt lgkmcnt(0)
	v_mfma_f32_16x16x32_bf16 v[28:31], v[144:147], v[188:191], v[28:31]
	v_mfma_f32_16x16x32_bf16 v[24:27], v[180:183], v[188:191], v[24:27]
	v_mfma_f32_16x16x32_bf16 v[20:23], v[144:147], v[196:199], v[20:23]
	v_mfma_f32_16x16x32_bf16 v[16:19], v[180:183], v[196:199], v[16:19]
	v_mfma_f32_16x16x32_bf16 v[12:15], v[144:147], v[204:207], v[12:15]
	v_mfma_f32_16x16x32_bf16 v[8:11], v[180:183], v[204:207], v[8:11]
	v_mfma_f32_16x16x32_bf16 v[4:7], v[144:147], v[212:215], v[4:7]
	v_mfma_f32_16x16x32_bf16 v[0:3], v[180:183], v[212:215], v[0:3]
	v_mfma_f32_16x16x32_bf16 v[28:31], v[156:159], v[192:195], v[28:31]
	v_mfma_f32_16x16x32_bf16 v[24:27], v[184:187], v[192:195], v[24:27]
	v_mfma_f32_16x16x32_bf16 v[20:23], v[156:159], v[200:203], v[20:23]
	v_mfma_f32_16x16x32_bf16 v[16:19], v[184:187], v[200:203], v[16:19]
	s_barrier
	v_mfma_f32_16x16x32_bf16 v[12:15], v[156:159], v[208:211], v[12:15]
	v_mfma_f32_16x16x32_bf16 v[8:11], v[184:187], v[208:211], v[8:11]
	v_mfma_f32_16x16x32_bf16 v[4:7], v[156:159], v[232:235], v[4:7]
	v_mfma_f32_16x16x32_bf16 v[0:3], v[184:187], v[232:235], v[0:3]
	s_setprio 0
	s_mov_b32 m0, s62
	v_lshl_add_u64 v[144:145], v[248:249], 0, s[8:9]
	global_load_lds_dwordx4 v[248:249], off
	s_mov_b32 m0, s63
	v_lshl_add_u64 v[146:147], v[250:251], 0, s[8:9]
	global_load_lds_dwordx4 v[250:251], off
	s_waitcnt vmcnt(6)
	s_barrier
	s_setprio 1
	v_mfma_f32_16x16x32_bf16 v[56:59], v[216:219], v[188:191], v[56:59]
	v_mfma_f32_16x16x32_bf16 v[60:63], v[224:227], v[188:191], v[60:63]
	v_mfma_f32_16x16x32_bf16 v[64:67], v[216:219], v[196:199], v[64:67]
	v_mfma_f32_16x16x32_bf16 v[72:75], v[224:227], v[196:199], v[72:75]
	v_mfma_f32_16x16x32_bf16 v[76:79], v[216:219], v[204:207], v[76:79]
	v_mfma_f32_16x16x32_bf16 v[80:83], v[224:227], v[204:207], v[80:83]
	v_mfma_f32_16x16x32_bf16 v[88:91], v[216:219], v[212:215], v[88:91]
	v_mfma_f32_16x16x32_bf16 v[92:95], v[224:227], v[212:215], v[92:95]
	v_mfma_f32_16x16x32_bf16 v[56:59], v[220:223], v[192:195], v[56:59]
	v_mfma_f32_16x16x32_bf16 v[60:63], v[228:231], v[192:195], v[60:63]
	v_mfma_f32_16x16x32_bf16 v[64:67], v[220:223], v[200:203], v[64:67]
	v_mfma_f32_16x16x32_bf16 v[72:75], v[228:231], v[200:203], v[72:75]
	s_barrier
	v_mfma_f32_16x16x32_bf16 v[76:79], v[220:223], v[208:211], v[76:79]
	v_mfma_f32_16x16x32_bf16 v[80:83], v[228:231], v[208:211], v[80:83]
	v_mfma_f32_16x16x32_bf16 v[88:91], v[220:223], v[232:235], v[88:91]
	v_mfma_f32_16x16x32_bf16 v[92:95], v[228:231], v[232:235], v[92:95]
	s_setprio 0
	s_add_i32 s57, s57, 2
	s_cmp_lt_i32 s57, s45
	s_cbranch_scc1 .LBB0_634
	s_add_i32 s0, s48, s33
	s_cmp_lt_i32 s0, s43
	s_cbranch_scc1 .Lg_last
	ds_read_b128 v[156:159], v152
	ds_read_b128 v[180:183], v152 offset:1024
	ds_read_b128 v[184:187], v152 offset:256
	ds_read_b128 v[188:191], v152 offset:1280
	s_mov_b32 m0, s56
	v_add_u32_e32 v153, s53, v151
	v_add_u32_e32 v154, s54, v151
	v_add_u32_e32 v155, s55, v151
	ds_read_b128 v[192:195], v128
	ds_read_b128 v[196:199], v128 offset:1024
	ds_read_b128 v[200:203], v153
	ds_read_b128 v[204:207], v153 offset:1024
	ds_read_b128 v[208:211], v154
	ds_read_b128 v[212:215], v154 offset:1024
	ds_read_b128 v[216:219], v155
	ds_read_b128 v[220:223], v155 offset:1024
	global_load_lds_dwordx4 v[132:133], off
	s_mov_b32 m0, s52
	v_lshl_add_u64 v[236:237], v[132:133], 0, s[8:9]
	global_load_lds_dwordx4 v[134:135], off
	v_lshl_add_u64 v[238:239], v[134:135], 0, s[8:9]
	s_andn2_b64 s[54:55], exec, s[2:3]
	s_cmp_lg_u64 s[54:55], 0
	s_cbranch_scc1 .Lwdma_skip_drain
	v_readlane_b32 s54, v252, 38
	v_readlane_b32 s55, v252, 39
	v_readlane_b32 s58, v252, 40
	v_readlane_b32 s59, v252, 41
	s_lshl_b32 s0, s47, 6
	s_and_b32 s0, s0, 0xfffffe00
	s_lshl_b32 s53, s50, 7
	s_add_i32 s0, s0, s53
	v_mbcnt_lo_u32_b32 v224, -1, 0
	v_mbcnt_hi_u32_b32 v224, -1, v224
	v_and_b32_e32 v230, 7, v224
	v_lshlrev_b32_e32 v230, 4, v230
	v_add_u32_e32 v230, s0, v230
	v_bfe_u32 v226, v224, 3, 2
	v_mul_u32_u24_e32 v228, 0x5800, v226
	v_add_u32_e32 v228, v228, v230
	v_mov_b32_e32 v229, 0
	v_mov_b32_e32 v231, 0
	v_lshl_add_u64 v[232:233], s[54:55], 0, v[228:229]
	v_lshl_add_u64 v[234:235], s[58:59], 0, v[230:231]
	v_cmp_eq_u32_e64 s[54:55], 3, v226
	s_add_i32 s0, s1, 0x21000
	s_mov_b32 m0, s0
	v_cndmask_b32_e64 v232, v232, v234, s[54:55]
	v_cndmask_b32_e64 v233, v233, v235, s[54:55]
	s_nop 1
	global_load_lds_dwordx4 v[232:233], off
; #define STAGE(P, q) do { GLDS16(q[0], (unsigned char*)(P) + wid * 1024); GLDS16(q[1], (unsigned char*)(P) + wid * 1024 + 8192); \
;     q[0] += 128; q[1] += 128; asm volatile("" : "+v"(q[0]), "+v"(q[1])); } while (0)
; #define LDA(dst, b, h) _Pragma("unroll") for (int m = 0; m < 4; ++m) _Pragma("unroll") for (int k = 0; k < 2; ++k) \
;     dst[m][k] = *(const bf16x8*)((const unsigned char*)SA(b, h) + lds_byte1(wr * 64 + m * 16 + fr, k * 32 + fq * 8))
; #define LDB(dst, b, h) _Pragma("unroll") for (int n = 0; n < 2; ++n) _Pragma("unroll") for (int k = 0; k < 2; ++k) \
;     dst[n][k] = *(const bf16x8*)((const unsigned char*)SB(b, h) + lds_byte1(wc * 32 + n * 16 + fr, k * 32 + fq * 8))
; #define MMA(ai, bj, At_, Bt_) do { __builtin_amdgcn_s_setprio(1); \
;     _Pragma("unroll") for (int m = 0; m < 4; ++m) _Pragma("unroll") for (int n = 0; n < 2; ++n) _Pragma("unroll") for (int k = 0; k < 2; ++k) \
;       acc[ai][bj][m][n] = mfma16(At_[m][k], Bt_[n][k], acc[ai][bj][m][n]); \
;     __builtin_amdgcn_s_setprio(0); } while (0)
; #define WAIT_V(n) asm volatile("s_waitcnt vmcnt(" #n ")" ::: "memory")
; #define WAIT_L(n) asm volatile("s_waitcnt lgkmcnt(" #n ")" ::: "memory")
; #define BAR __builtin_amdgcn_s_barrier()
; DEV void gemm_tile(const u16* __restrict__ A, const u16* __restrict__ Bt, u16* __restrict__ C, int N, int K,
;                    int brow, int bcol, unsigned char* smem, int epi, const GateEpi& ge) {
;     ...
;   { LDB(B0, 0, 0); LDA(At, 0, 0); STAGE(SA(1, 1), qA1);
;     BAR; WAIT_L(0); MMA(0, 0, At, B0); BAR;
;     LDB(B1, 0, 1); BAR; WAIT_L(0); MMA(0, 1, At, B1); BAR;
;     LDA(At, 0, 1); WAIT_V(4); BAR; WAIT_L(0); MMA(1, 0, At, B0); MMA(1, 1, At, B1); BAR; }
;   { LDB(B0, 1, 0); LDA(At, 1, 0); WAIT_V(2); BAR; WAIT_L(0); MMA(0, 0, At, B0); BAR;
;     LDB(B1, 1, 1); WAIT_V(0); BAR; WAIT_L(0); MMA(0, 1, At, B1); BAR;
;     LDA(At, 1, 1); BAR; WAIT_L(0); MMA(1, 0, At, B0); MMA(1, 1, At, B1); BAR; }
.Lwdma_skip_drain:
	s_waitcnt lgkmcnt(8)
	s_barrier
	s_waitcnt lgkmcnt(0)
	s_setprio 1
	s_waitcnt lgkmcnt(0)
	v_mfma_f32_16x16x32_bf16 v[124:127], v[156:159], v[192:195], v[124:127]
	v_mfma_f32_16x16x32_bf16 v[120:123], v[184:187], v[192:195], v[120:123]
	v_mfma_f32_16x16x32_bf16 v[116:119], v[156:159], v[200:203], v[116:119]
	v_mfma_f32_16x16x32_bf16 v[112:115], v[184:187], v[200:203], v[112:115]
	v_mfma_f32_16x16x32_bf16 v[108:111], v[156:159], v[208:211], v[108:111]
	v_mfma_f32_16x16x32_bf16 v[104:107], v[184:187], v[208:211], v[104:107]
	v_mfma_f32_16x16x32_bf16 v[100:103], v[156:159], v[216:219], v[100:103]
	v_mfma_f32_16x16x32_bf16 v[96:99], v[184:187], v[216:219], v[96:99]
	v_mfma_f32_16x16x32_bf16 v[124:127], v[180:183], v[196:199], v[124:127]
	v_mfma_f32_16x16x32_bf16 v[120:123], v[188:191], v[196:199], v[120:123]
	v_mfma_f32_16x16x32_bf16 v[116:119], v[180:183], v[204:207], v[116:119]
	v_mfma_f32_16x16x32_bf16 v[112:115], v[188:191], v[204:207], v[112:115]
	s_barrier
	v_mfma_f32_16x16x32_bf16 v[108:111], v[180:183], v[212:215], v[108:111]
	v_mfma_f32_16x16x32_bf16 v[104:107], v[188:191], v[212:215], v[104:107]
	v_mfma_f32_16x16x32_bf16 v[100:103], v[180:183], v[220:223], v[100:103]
	v_mfma_f32_16x16x32_bf16 v[96:99], v[188:191], v[220:223], v[96:99]
	s_setprio 0
	s_mov_b32 m0, s4
	ds_read_b128 v[132:135], v150
	ds_read_b128 v[224:227], v150 offset:1024
	ds_read_b128 v[228:231], v150 offset:256
	ds_read_b128 v[232:235], v150 offset:1280
	s_mov_b32 m0, s5
	v_lshl_add_u64 v[240:241], v[136:137], 0, s[8:9]
	v_lshl_add_u64 v[242:243], v[138:139], 0, s[8:9]
	s_barrier
	s_waitcnt lgkmcnt(0)
	s_setprio 1
	s_waitcnt lgkmcnt(0)
	v_mfma_f32_16x16x32_bf16 v[84:87], v[132:135], v[192:195], v[84:87]
	v_mfma_f32_16x16x32_bf16 v[68:71], v[228:231], v[192:195], v[68:71]
	v_mfma_f32_16x16x32_bf16 v[52:55], v[132:135], v[200:203], v[52:55]
	v_mfma_f32_16x16x32_bf16 v[48:51], v[228:231], v[200:203], v[48:51]
	v_mfma_f32_16x16x32_bf16 v[44:47], v[132:135], v[208:211], v[44:47]
	v_mfma_f32_16x16x32_bf16 v[40:43], v[228:231], v[208:211], v[40:43]
	v_mfma_f32_16x16x32_bf16 v[36:39], v[132:135], v[216:219], v[36:39]
	v_mfma_f32_16x16x32_bf16 v[32:35], v[228:231], v[216:219], v[32:35]
	v_mfma_f32_16x16x32_bf16 v[84:87], v[224:227], v[196:199], v[84:87]
	v_mfma_f32_16x16x32_bf16 v[68:71], v[232:235], v[196:199], v[68:71]
	v_mfma_f32_16x16x32_bf16 v[52:55], v[224:227], v[204:207], v[52:55]
	v_mfma_f32_16x16x32_bf16 v[48:51], v[232:235], v[204:207], v[48:51]
	s_barrier
	v_mfma_f32_16x16x32_bf16 v[44:47], v[224:227], v[212:215], v[44:47]
	v_mfma_f32_16x16x32_bf16 v[40:43], v[232:235], v[212:215], v[40:43]
	v_mfma_f32_16x16x32_bf16 v[36:39], v[224:227], v[220:223], v[36:39]
	v_mfma_f32_16x16x32_bf16 v[32:35], v[232:235], v[220:223], v[32:35]
	s_setprio 0
	s_mov_b32 m0, s1
	ds_read_b128 v[136:139], v128 offset:16384
	ds_read_b128 v[192:195], v128 offset:17408
	ds_read_b128 v[196:199], v153 offset:16384
	ds_read_b128 v[200:203], v153 offset:17408
	ds_read_b128 v[204:207], v154 offset:16384
	ds_read_b128 v[208:211], v154 offset:17408
	ds_read_b128 v[212:215], v155 offset:16384
	ds_read_b128 v[216:219], v155 offset:17408
	s_mov_b32 m0, s6
	v_lshl_add_u64 v[244:245], v[140:141], 0, s[8:9]
	v_lshl_add_u64 v[246:247], v[142:143], 0, s[8:9]
	s_barrier
	s_waitcnt lgkmcnt(0)
	s_setprio 1
	s_waitcnt lgkmcnt(0)
	v_mfma_f32_16x16x32_bf16 v[28:31], v[156:159], v[136:139], v[28:31]
	v_mfma_f32_16x16x32_bf16 v[24:27], v[184:187], v[136:139], v[24:27]
	v_mfma_f32_16x16x32_bf16 v[20:23], v[156:159], v[196:199], v[20:23]
	v_mfma_f32_16x16x32_bf16 v[16:19], v[184:187], v[196:199], v[16:19]
	v_mfma_f32_16x16x32_bf16 v[12:15], v[156:159], v[204:207], v[12:15]
	v_mfma_f32_16x16x32_bf16 v[8:11], v[184:187], v[204:207], v[8:11]
	v_mfma_f32_16x16x32_bf16 v[4:7], v[156:159], v[212:215], v[4:7]
	v_mfma_f32_16x16x32_bf16 v[0:3], v[184:187], v[212:215], v[0:3]
	v_mfma_f32_16x16x32_bf16 v[28:31], v[180:183], v[192:195], v[28:31]
	v_mfma_f32_16x16x32_bf16 v[24:27], v[188:191], v[192:195], v[24:27]
	v_mfma_f32_16x16x32_bf16 v[20:23], v[180:183], v[200:203], v[20:23]
	v_mfma_f32_16x16x32_bf16 v[16:19], v[188:191], v[200:203], v[16:19]
	s_barrier
	v_mfma_f32_16x16x32_bf16 v[12:15], v[180:183], v[208:211], v[12:15]
	v_mfma_f32_16x16x32_bf16 v[8:11], v[188:191], v[208:211], v[8:11]
	v_mfma_f32_16x16x32_bf16 v[4:7], v[180:183], v[216:219], v[4:7]
	v_mfma_f32_16x16x32_bf16 v[0:3], v[188:191], v[216:219], v[0:3]
	s_setprio 0
	s_mov_b32 m0, s7
	v_lshl_add_u64 v[248:249], v[144:145], 0, s[8:9]
	s_mov_b32 m0, s35
	v_lshl_add_u64 v[250:251], v[146:147], 0, s[8:9]
	s_waitcnt vmcnt(0)
	s_barrier
	s_setprio 1
	v_mfma_f32_16x16x32_bf16 v[56:59], v[132:135], v[136:139], v[56:59]
	v_mfma_f32_16x16x32_bf16 v[60:63], v[228:231], v[136:139], v[60:63]
	v_mfma_f32_16x16x32_bf16 v[64:67], v[132:135], v[196:199], v[64:67]
	v_mfma_f32_16x16x32_bf16 v[72:75], v[228:231], v[196:199], v[72:75]
	v_mfma_f32_16x16x32_bf16 v[76:79], v[132:135], v[204:207], v[76:79]
	v_mfma_f32_16x16x32_bf16 v[80:83], v[228:231], v[204:207], v[80:83]
	v_mfma_f32_16x16x32_bf16 v[88:91], v[132:135], v[212:215], v[88:91]
	v_mfma_f32_16x16x32_bf16 v[92:95], v[228:231], v[212:215], v[92:95]
	v_mfma_f32_16x16x32_bf16 v[56:59], v[224:227], v[192:195], v[56:59]
	v_mfma_f32_16x16x32_bf16 v[60:63], v[232:235], v[192:195], v[60:63]
	v_mfma_f32_16x16x32_bf16 v[64:67], v[224:227], v[200:203], v[64:67]
	v_mfma_f32_16x16x32_bf16 v[72:75], v[232:235], v[200:203], v[72:75]
	s_barrier
; #define LDA(dst, b, h) _Pragma("unroll") for (int m = 0; m < 4; ++m) _Pragma("unroll") for (int k = 0; k < 2; ++k) \
;     dst[m][k] = *(const bf16x8*)((const unsigned char*)SA(b, h) + lds_byte1(wr * 64 + m * 16 + fr, k * 32 + fq * 8))
; #define LDB(dst, b, h) _Pragma("unroll") for (int n = 0; n < 2; ++n) _Pragma("unroll") for (int k = 0; k < 2; ++k) \
;     dst[n][k] = *(const bf16x8*)((const unsigned char*)SB(b, h) + lds_byte1(wc * 32 + n * 16 + fr, k * 32 + fq * 8))
; #define MMA(ai, bj, At_, Bt_) do { __builtin_amdgcn_s_setprio(1); \
;     _Pragma("unroll") for (int m = 0; m < 4; ++m) _Pragma("unroll") for (int n = 0; n < 2; ++n) _Pragma("unroll") for (int k = 0; k < 2; ++k) \
;       acc[ai][bj][m][n] = mfma16(At_[m][k], Bt_[n][k], acc[ai][bj][m][n]); \
;     __builtin_amdgcn_s_setprio(0); } while (0)
; #define WAIT_V(n) asm volatile("s_waitcnt vmcnt(" #n ")" ::: "memory")
; #define WAIT_L(n) asm volatile("s_waitcnt lgkmcnt(" #n ")" ::: "memory")
; #define BAR __builtin_amdgcn_s_barrier()
; DEV void gemm_tile(const u16* __restrict__ A, const u16* __restrict__ Bt, u16* __restrict__ C, int N, int K,
;                    int brow, int bcol, unsigned char* smem, int epi, const GateEpi& ge) {
;     ...
;     LDB(B1, 0, 1); BAR; WAIT_L(0); MMA(0, 1, At, B1); BAR;
;     LDA(At, 0, 1); WAIT_V(4); BAR; WAIT_L(0); MMA(1, 0, At, B0); MMA(1, 1, At, B1); BAR; }
;   { LDB(B0, 1, 0); LDA(At, 1, 0); WAIT_V(2); BAR; WAIT_L(0); MMA(0, 0, At, B0); BAR;
;     LDB(B1, 1, 1); WAIT_V(0); BAR; WAIT_L(0); MMA(0, 1, At, B1); BAR;
;     LDA(At, 1, 1); BAR; WAIT_L(0); MMA(1, 0, At, B0); MMA(1, 1, At, B1); BAR; }
	v_mfma_f32_16x16x32_bf16 v[76:79], v[224:227], v[208:211], v[76:79]
	v_mfma_f32_16x16x32_bf16 v[80:83], v[232:235], v[208:211], v[80:83]
	v_mfma_f32_16x16x32_bf16 v[88:91], v[224:227], v[216:219], v[88:91]
	v_mfma_f32_16x16x32_bf16 v[92:95], v[232:235], v[216:219], v[92:95]
	s_setprio 0
	ds_read_b128 v[144:147], v149
	ds_read_b128 v[156:159], v149 offset:1024
	ds_read_b128 v[180:183], v149 offset:256
	ds_read_b128 v[184:187], v149 offset:1280
	s_mov_b32 m0, s41
	ds_read_b128 v[140:143], v128 offset:32768
	ds_read_b128 v[188:191], v128 offset:33792
	ds_read_b128 v[192:195], v153 offset:32768
	ds_read_b128 v[196:199], v153 offset:33792
	ds_read_b128 v[200:203], v154 offset:32768
	ds_read_b128 v[204:207], v154 offset:33792
	ds_read_b128 v[208:211], v155 offset:32768
	ds_read_b128 v[212:215], v155 offset:33792
	s_mov_b32 m0, vcc_lo
	v_lshl_add_u64 v[132:133], v[236:237], 0, s[8:9]
	v_lshl_add_u64 v[134:135], v[238:239], 0, s[8:9]
	s_waitcnt lgkmcnt(8)
	s_barrier
	s_waitcnt lgkmcnt(0)
	s_setprio 1
	s_waitcnt lgkmcnt(0)
	v_mfma_f32_16x16x32_bf16 v[124:127], v[144:147], v[140:143], v[124:127]
	v_mfma_f32_16x16x32_bf16 v[120:123], v[180:183], v[140:143], v[120:123]
	v_mfma_f32_16x16x32_bf16 v[116:119], v[144:147], v[192:195], v[116:119]
	v_mfma_f32_16x16x32_bf16 v[112:115], v[180:183], v[192:195], v[112:115]
	v_mfma_f32_16x16x32_bf16 v[108:111], v[144:147], v[200:203], v[108:111]
	v_mfma_f32_16x16x32_bf16 v[104:107], v[180:183], v[200:203], v[104:107]
	v_mfma_f32_16x16x32_bf16 v[100:103], v[144:147], v[208:211], v[100:103]
	v_mfma_f32_16x16x32_bf16 v[96:99], v[180:183], v[208:211], v[96:99]
	v_mfma_f32_16x16x32_bf16 v[124:127], v[156:159], v[188:191], v[124:127]
	v_mfma_f32_16x16x32_bf16 v[120:123], v[184:187], v[188:191], v[120:123]
	v_mfma_f32_16x16x32_bf16 v[116:119], v[156:159], v[196:199], v[116:119]
	v_mfma_f32_16x16x32_bf16 v[112:115], v[184:187], v[196:199], v[112:115]
	s_barrier
	v_mfma_f32_16x16x32_bf16 v[108:111], v[156:159], v[204:207], v[108:111]
	v_mfma_f32_16x16x32_bf16 v[104:107], v[184:187], v[204:207], v[104:107]
	v_mfma_f32_16x16x32_bf16 v[100:103], v[156:159], v[212:215], v[100:103]
	v_mfma_f32_16x16x32_bf16 v[96:99], v[184:187], v[212:215], v[96:99]
	s_setprio 0
	s_mov_b32 m0, vcc_hi
	ds_read_b128 v[216:219], v148
	ds_read_b128 v[220:223], v148 offset:1024
	ds_read_b128 v[224:227], v148 offset:256
	ds_read_b128 v[228:231], v148 offset:1280
	s_mov_b32 m0, s28
	v_lshl_add_u64 v[136:137], v[240:241], 0, s[8:9]
	v_lshl_add_u64 v[138:139], v[242:243], 0, s[8:9]
	s_barrier
	s_waitcnt lgkmcnt(0)
	s_setprio 1
	s_waitcnt lgkmcnt(0)
	v_mfma_f32_16x16x32_bf16 v[84:87], v[216:219], v[140:143], v[84:87]
	v_mfma_f32_16x16x32_bf16 v[68:71], v[224:227], v[140:143], v[68:71]
	v_mfma_f32_16x16x32_bf16 v[52:55], v[216:219], v[192:195], v[52:55]
	v_mfma_f32_16x16x32_bf16 v[48:51], v[224:227], v[192:195], v[48:51]
	v_mfma_f32_16x16x32_bf16 v[44:47], v[216:219], v[200:203], v[44:47]
	v_mfma_f32_16x16x32_bf16 v[40:43], v[224:227], v[200:203], v[40:43]
	v_mfma_f32_16x16x32_bf16 v[36:39], v[216:219], v[208:211], v[36:39]
	v_mfma_f32_16x16x32_bf16 v[32:35], v[224:227], v[208:211], v[32:35]
	v_mfma_f32_16x16x32_bf16 v[84:87], v[220:223], v[188:191], v[84:87]
	v_mfma_f32_16x16x32_bf16 v[68:71], v[228:231], v[188:191], v[68:71]
	v_mfma_f32_16x16x32_bf16 v[52:55], v[220:223], v[196:199], v[52:55]
	v_mfma_f32_16x16x32_bf16 v[48:51], v[228:231], v[196:199], v[48:51]
	s_barrier
	v_mfma_f32_16x16x32_bf16 v[44:47], v[220:223], v[204:207], v[44:47]
	v_mfma_f32_16x16x32_bf16 v[40:43], v[228:231], v[204:207], v[40:43]
	v_mfma_f32_16x16x32_bf16 v[36:39], v[220:223], v[212:215], v[36:39]
	v_mfma_f32_16x16x32_bf16 v[32:35], v[228:231], v[212:215], v[32:35]
	s_setprio 0
	s_mov_b32 m0, s94
	ds_read_b128 v[188:191], v128 offset:49152
	ds_read_b128 v[192:195], v128 offset:50176
	ds_read_b128 v[196:199], v153 offset:49152
	ds_read_b128 v[200:203], v153 offset:50176
	ds_read_b128 v[204:207], v154 offset:49152
	ds_read_b128 v[208:211], v154 offset:50176
	ds_read_b128 v[212:215], v155 offset:49152
	ds_read_b128 v[232:235], v155 offset:50176
	s_mov_b32 m0, s95
	v_lshl_add_u64 v[140:141], v[244:245], 0, s[8:9]
	v_lshl_add_u64 v[142:143], v[246:247], 0, s[8:9]
	s_barrier
	s_waitcnt lgkmcnt(0)
	s_setprio 1
	s_waitcnt lgkmcnt(0)
	v_mfma_f32_16x16x32_bf16 v[28:31], v[144:147], v[188:191], v[28:31]
	v_mfma_f32_16x16x32_bf16 v[24:27], v[180:183], v[188:191], v[24:27]
	v_mfma_f32_16x16x32_bf16 v[20:23], v[144:147], v[196:199], v[20:23]
	v_mfma_f32_16x16x32_bf16 v[16:19], v[180:183], v[196:199], v[16:19]
	v_mfma_f32_16x16x32_bf16 v[12:15], v[144:147], v[204:207], v[12:15]
	v_mfma_f32_16x16x32_bf16 v[8:11], v[180:183], v[204:207], v[8:11]
	v_mfma_f32_16x16x32_bf16 v[4:7], v[144:147], v[212:215], v[4:7]
	v_mfma_f32_16x16x32_bf16 v[0:3], v[180:183], v[212:215], v[0:3]
	v_mfma_f32_16x16x32_bf16 v[28:31], v[156:159], v[192:195], v[28:31]
	v_mfma_f32_16x16x32_bf16 v[24:27], v[184:187], v[192:195], v[24:27]
	v_mfma_f32_16x16x32_bf16 v[20:23], v[156:159], v[200:203], v[20:23]
	v_mfma_f32_16x16x32_bf16 v[16:19], v[184:187], v[200:203], v[16:19]
	s_barrier
	v_mfma_f32_16x16x32_bf16 v[12:15], v[156:159], v[208:211], v[12:15]
	v_mfma_f32_16x16x32_bf16 v[8:11], v[184:187], v[208:211], v[8:11]
	v_mfma_f32_16x16x32_bf16 v[4:7], v[156:159], v[232:235], v[4:7]
	v_mfma_f32_16x16x32_bf16 v[0:3], v[184:187], v[232:235], v[0:3]
	s_setprio 0
	s_mov_b32 m0, s62
	v_lshl_add_u64 v[144:145], v[248:249], 0, s[8:9]
	s_mov_b32 m0, s63
	v_lshl_add_u64 v[146:147], v[250:251], 0, s[8:9]
	s_waitcnt vmcnt(0)
	s_barrier
	s_setprio 1
	v_mfma_f32_16x16x32_bf16 v[56:59], v[216:219], v[188:191], v[56:59]
	v_mfma_f32_16x16x32_bf16 v[60:63], v[224:227], v[188:191], v[60:63]
	v_mfma_f32_16x16x32_bf16 v[64:67], v[216:219], v[196:199], v[64:67]
	v_mfma_f32_16x16x32_bf16 v[72:75], v[224:227], v[196:199], v[72:75]
	v_mfma_f32_16x16x32_bf16 v[76:79], v[216:219], v[204:207], v[76:79]
	v_mfma_f32_16x16x32_bf16 v[80:83], v[224:227], v[204:207], v[80:83]
	v_mfma_f32_16x16x32_bf16 v[88:91], v[216:219], v[212:215], v[88:91]
	v_mfma_f32_16x16x32_bf16 v[92:95], v[224:227], v[212:215], v[92:95]
	v_mfma_f32_16x16x32_bf16 v[56:59], v[220:223], v[192:195], v[56:59]
	v_mfma_f32_16x16x32_bf16 v[60:63], v[228:231], v[192:195], v[60:63]
	v_mfma_f32_16x16x32_bf16 v[64:67], v[220:223], v[200:203], v[64:67]
	v_mfma_f32_16x16x32_bf16 v[72:75], v[228:231], v[200:203], v[72:75]
	s_barrier
	v_mfma_f32_16x16x32_bf16 v[76:79], v[220:223], v[208:211], v[76:79]
	v_mfma_f32_16x16x32_bf16 v[80:83], v[228:231], v[208:211], v[80:83]
	v_mfma_f32_16x16x32_bf16 v[88:91], v[220:223], v[232:235], v[88:91]
	v_mfma_f32_16x16x32_bf16 v[92:95], v[228:231], v[232:235], v[92:95]
	s_setprio 0
	s_mov_b32 s63, 0
	s_branch .Lg_unstag

; #define STAGE(P, q) do { GLDS16(q[0], (unsigned char*)(P) + wid * 1024); GLDS16(q[1], (unsigned char*)(P) + wid * 1024 + 8192); \
;     q[0] += 128; q[1] += 128; asm volatile("" : "+v"(q[0]), "+v"(q[1])); } while (0)
; #define LDA(dst, b, h) _Pragma("unroll") for (int m = 0; m < 4; ++m) _Pragma("unroll") for (int k = 0; k < 2; ++k) \
;     dst[m][k] = *(const bf16x8*)((const unsigned char*)SA(b, h) + lds_byte1(wr * 64 + m * 16 + fr, k * 32 + fq * 8))
; #define LDB(dst, b, h) _Pragma("unroll") for (int n = 0; n < 2; ++n) _Pragma("unroll") for (int k = 0; k < 2; ++k) \
;     dst[n][k] = *(const bf16x8*)((const unsigned char*)SB(b, h) + lds_byte1(wc * 32 + n * 16 + fr, k * 32 + fq * 8))
; #define MMA(ai, bj, At_, Bt_) do { __builtin_amdgcn_s_setprio(1); \
;     _Pragma("unroll") for (int m = 0; m < 4; ++m) _Pragma("unroll") for (int n = 0; n < 2; ++n) _Pragma("unroll") for (int k = 0; k < 2; ++k) \
;       acc[ai][bj][m][n] = mfma16(At_[m][k], Bt_[n][k], acc[ai][bj][m][n]); \
;     __builtin_amdgcn_s_setprio(0); } while (0)
; #define WAIT_V(n) asm volatile("s_waitcnt vmcnt(" #n ")" ::: "memory")
; #define WAIT_L(n) asm volatile("s_waitcnt lgkmcnt(" #n ")" ::: "memory")
; #define BAR __builtin_amdgcn_s_barrier()
; DEV void gemm_tile(const u16* __restrict__ A, const u16* __restrict__ Bt, u16* __restrict__ C, int N, int K,
;                    int brow, int bcol, unsigned char* smem, int epi, const GateEpi& ge) {
;     ...
;   STAGE(SB(0, 0), qB0); STAGE(SA(0, 0), qA0);
;   STAGE(SB(0, 1), qB1); STAGE(SA(0, 1), qA1);
;   if (wr == 1) BAR;
;   WAIT_V(4); BAR;
;   STAGE(SB(1, 0), qB0); STAGE(SA(1, 0), qA0); STAGE(SB(1, 1), qB1);
;     ...
;   { LDB(B0, 0, 0); LDA(At, 0, 0); STAGE(SA(1, 1), qA1);
;     BAR; WAIT_L(0); MMA(0, 0, At, B0); BAR;
;     LDB(B1, 0, 1); BAR; WAIT_L(0); MMA(0, 1, At, B1); BAR;
;     LDA(At, 0, 1); WAIT_V(4); BAR; WAIT_L(0); MMA(1, 0, At, B0); MMA(1, 1, At, B1); BAR; }
;   { LDB(B0, 1, 0); LDA(At, 1, 0); WAIT_V(2); BAR; WAIT_L(0); MMA(0, 0, At, B0); BAR;
;     LDB(B1, 1, 1); WAIT_V(0); BAR; WAIT_L(0); MMA(0, 1, At, B1); BAR;
;     LDA(At, 1, 1); BAR; WAIT_L(0); MMA(1, 0, At, B0); MMA(1, 1, At, B1); BAR; }
.Lwdma_skip_last:
	s_waitcnt lgkmcnt(8)
	s_barrier
	s_waitcnt lgkmcnt(0)
	s_setprio 1
	s_waitcnt lgkmcnt(0)
	v_mfma_f32_16x16x32_bf16 v[124:127], v[156:159], v[192:195], v[124:127]
	v_mfma_f32_16x16x32_bf16 v[120:123], v[184:187], v[192:195], v[120:123]
	v_mfma_f32_16x16x32_bf16 v[116:119], v[156:159], v[200:203], v[116:119]
	v_mfma_f32_16x16x32_bf16 v[112:115], v[184:187], v[200:203], v[112:115]
	v_mfma_f32_16x16x32_bf16 v[108:111], v[156:159], v[208:211], v[108:111]
	v_mfma_f32_16x16x32_bf16 v[104:107], v[184:187], v[208:211], v[104:107]
	v_mfma_f32_16x16x32_bf16 v[100:103], v[156:159], v[216:219], v[100:103]
	v_mfma_f32_16x16x32_bf16 v[96:99], v[184:187], v[216:219], v[96:99]
	v_mfma_f32_16x16x32_bf16 v[124:127], v[180:183], v[196:199], v[124:127]
	v_mfma_f32_16x16x32_bf16 v[120:123], v[188:191], v[196:199], v[120:123]
	v_mfma_f32_16x16x32_bf16 v[116:119], v[180:183], v[204:207], v[116:119]
	v_mfma_f32_16x16x32_bf16 v[112:115], v[188:191], v[204:207], v[112:115]
	s_barrier
	v_mfma_f32_16x16x32_bf16 v[108:111], v[180:183], v[212:215], v[108:111]
	v_mfma_f32_16x16x32_bf16 v[104:107], v[188:191], v[212:215], v[104:107]
	v_mfma_f32_16x16x32_bf16 v[100:103], v[180:183], v[220:223], v[100:103]
	v_mfma_f32_16x16x32_bf16 v[96:99], v[188:191], v[220:223], v[96:99]
	s_setprio 0
	s_mov_b32 m0, s4
	ds_read_b128 v[132:135], v150
	ds_read_b128 v[224:227], v150 offset:1024
	ds_read_b128 v[228:231], v150 offset:256
	ds_read_b128 v[232:235], v150 offset:1280
	global_load_lds_dwordx4 v[136:137], off
	s_mov_b32 m0, s5
	v_lshl_add_u64 v[240:241], v[136:137], 0, s[8:9]
	global_load_lds_dwordx4 v[138:139], off
	v_lshl_add_u64 v[242:243], v[138:139], 0, s[8:9]
	s_barrier
	s_waitcnt lgkmcnt(0)
	s_setprio 1
	s_waitcnt lgkmcnt(0)
	v_mfma_f32_16x16x32_bf16 v[84:87], v[132:135], v[192:195], v[84:87]
	v_mfma_f32_16x16x32_bf16 v[68:71], v[228:231], v[192:195], v[68:71]
	v_mfma_f32_16x16x32_bf16 v[52:55], v[132:135], v[200:203], v[52:55]
	v_mfma_f32_16x16x32_bf16 v[48:51], v[228:231], v[200:203], v[48:51]
	v_mfma_f32_16x16x32_bf16 v[44:47], v[132:135], v[208:211], v[44:47]
	v_mfma_f32_16x16x32_bf16 v[40:43], v[228:231], v[208:211], v[40:43]
	v_mfma_f32_16x16x32_bf16 v[36:39], v[132:135], v[216:219], v[36:39]
	v_mfma_f32_16x16x32_bf16 v[32:35], v[228:231], v[216:219], v[32:35]
	v_mfma_f32_16x16x32_bf16 v[84:87], v[224:227], v[196:199], v[84:87]
	v_mfma_f32_16x16x32_bf16 v[68:71], v[232:235], v[196:199], v[68:71]
	v_mfma_f32_16x16x32_bf16 v[52:55], v[224:227], v[204:207], v[52:55]
	v_mfma_f32_16x16x32_bf16 v[48:51], v[232:235], v[204:207], v[48:51]
	s_barrier
	v_mfma_f32_16x16x32_bf16 v[44:47], v[224:227], v[212:215], v[44:47]
	v_mfma_f32_16x16x32_bf16 v[40:43], v[232:235], v[212:215], v[40:43]
	v_mfma_f32_16x16x32_bf16 v[36:39], v[224:227], v[220:223], v[36:39]
	v_mfma_f32_16x16x32_bf16 v[32:35], v[232:235], v[220:223], v[32:35]
	s_setprio 0
	s_mov_b32 m0, s1
	ds_read_b128 v[136:139], v128 offset:16384
	ds_read_b128 v[192:195], v128 offset:17408
	ds_read_b128 v[196:199], v153 offset:16384
	ds_read_b128 v[200:203], v153 offset:17408
	ds_read_b128 v[204:207], v154 offset:16384
	ds_read_b128 v[208:211], v154 offset:17408
	ds_read_b128 v[212:215], v155 offset:16384
	ds_read_b128 v[216:219], v155 offset:17408
	global_load_lds_dwordx4 v[140:141], off
	s_mov_b32 m0, s6
	v_lshl_add_u64 v[244:245], v[140:141], 0, s[8:9]
	global_load_lds_dwordx4 v[142:143], off
	v_lshl_add_u64 v[246:247], v[142:143], 0, s[8:9]
	s_barrier
	s_waitcnt lgkmcnt(0)
	s_setprio 1
	s_waitcnt lgkmcnt(0)
	v_mfma_f32_16x16x32_bf16 v[28:31], v[156:159], v[136:139], v[28:31]
	v_mfma_f32_16x16x32_bf16 v[24:27], v[184:187], v[136:139], v[24:27]
	v_mfma_f32_16x16x32_bf16 v[20:23], v[156:159], v[196:199], v[20:23]
	v_mfma_f32_16x16x32_bf16 v[16:19], v[184:187], v[196:199], v[16:19]
	v_mfma_f32_16x16x32_bf16 v[12:15], v[156:159], v[204:207], v[12:15]
	v_mfma_f32_16x16x32_bf16 v[8:11], v[184:187], v[204:207], v[8:11]
	v_mfma_f32_16x16x32_bf16 v[4:7], v[156:159], v[212:215], v[4:7]
	v_mfma_f32_16x16x32_bf16 v[0:3], v[184:187], v[212:215], v[0:3]
	v_mfma_f32_16x16x32_bf16 v[28:31], v[180:183], v[192:195], v[28:31]
	v_mfma_f32_16x16x32_bf16 v[24:27], v[188:191], v[192:195], v[24:27]
	v_mfma_f32_16x16x32_bf16 v[20:23], v[180:183], v[200:203], v[20:23]
	v_mfma_f32_16x16x32_bf16 v[16:19], v[188:191], v[200:203], v[16:19]
	s_barrier
	v_mfma_f32_16x16x32_bf16 v[12:15], v[180:183], v[208:211], v[12:15]
	v_mfma_f32_16x16x32_bf16 v[8:11], v[188:191], v[208:211], v[8:11]
	v_mfma_f32_16x16x32_bf16 v[4:7], v[180:183], v[216:219], v[4:7]
	v_mfma_f32_16x16x32_bf16 v[0:3], v[188:191], v[216:219], v[0:3]
	s_setprio 0
	s_mov_b32 m0, s7
	v_lshl_add_u64 v[248:249], v[144:145], 0, s[8:9]
	global_load_lds_dwordx4 v[144:145], off
	s_mov_b32 m0, s35
	v_lshl_add_u64 v[250:251], v[146:147], 0, s[8:9]
	global_load_lds_dwordx4 v[146:147], off
	s_waitcnt vmcnt(6)
	s_barrier
	s_setprio 1
	v_mfma_f32_16x16x32_bf16 v[56:59], v[132:135], v[136:139], v[56:59]
	v_mfma_f32_16x16x32_bf16 v[60:63], v[228:231], v[136:139], v[60:63]
	v_mfma_f32_16x16x32_bf16 v[64:67], v[132:135], v[196:199], v[64:67]
	v_mfma_f32_16x16x32_bf16 v[72:75], v[228:231], v[196:199], v[72:75]
	v_mfma_f32_16x16x32_bf16 v[76:79], v[132:135], v[204:207], v[76:79]
	v_mfma_f32_16x16x32_bf16 v[80:83], v[228:231], v[204:207], v[80:83]
	v_mfma_f32_16x16x32_bf16 v[88:91], v[132:135], v[212:215], v[88:91]
	v_mfma_f32_16x16x32_bf16 v[92:95], v[228:231], v[212:215], v[92:95]
	v_mfma_f32_16x16x32_bf16 v[56:59], v[224:227], v[192:195], v[56:59]
	v_mfma_f32_16x16x32_bf16 v[60:63], v[232:235], v[192:195], v[60:63]
	v_mfma_f32_16x16x32_bf16 v[64:67], v[224:227], v[200:203], v[64:67]
	v_mfma_f32_16x16x32_bf16 v[72:75], v[232:235], v[200:203], v[72:75]
	s_barrier
; #define STAGE(P, q) do { GLDS16(q[0], (unsigned char*)(P) + wid * 1024); GLDS16(q[1], (unsigned char*)(P) + wid * 1024 + 8192); \
;     q[0] += 128; q[1] += 128; asm volatile("" : "+v"(q[0]), "+v"(q[1])); } while (0)
; #define LDA(dst, b, h) _Pragma("unroll") for (int m = 0; m < 4; ++m) _Pragma("unroll") for (int k = 0; k < 2; ++k) \
;     dst[m][k] = *(const bf16x8*)((const unsigned char*)SA(b, h) + lds_byte1(wr * 64 + m * 16 + fr, k * 32 + fq * 8))
; #define LDB(dst, b, h) _Pragma("unroll") for (int n = 0; n < 2; ++n) _Pragma("unroll") for (int k = 0; k < 2; ++k) \
;     dst[n][k] = *(const bf16x8*)((const unsigned char*)SB(b, h) + lds_byte1(wc * 32 + n * 16 + fr, k * 32 + fq * 8))
; #define MMA(ai, bj, At_, Bt_) do { __builtin_amdgcn_s_setprio(1); \
;     _Pragma("unroll") for (int m = 0; m < 4; ++m) _Pragma("unroll") for (int n = 0; n < 2; ++n) _Pragma("unroll") for (int k = 0; k < 2; ++k) \
;       acc[ai][bj][m][n] = mfma16(At_[m][k], Bt_[n][k], acc[ai][bj][m][n]); \
;     __builtin_amdgcn_s_setprio(0); } while (0)
; #define WAIT_V(n) asm volatile("s_waitcnt vmcnt(" #n ")" ::: "memory")
; #define WAIT_L(n) asm volatile("s_waitcnt lgkmcnt(" #n ")" ::: "memory")
; #define BAR __builtin_amdgcn_s_barrier()
; DEV void gemm_tile(const u16* __restrict__ A, const u16* __restrict__ Bt, u16* __restrict__ C, int N, int K,
;                    int brow, int bcol, unsigned char* smem, int epi, const GateEpi& ge) {
;     ...
;   STAGE(SB(1, 0), qB0); STAGE(SA(1, 0), qA0); STAGE(SB(1, 1), qB1);
;   WAIT_V(6); BAR;
;     ...
;     LDB(B1, 0, 1); BAR; WAIT_L(0); MMA(0, 1, At, B1); BAR;
;     LDA(At, 0, 1); WAIT_V(4); BAR; WAIT_L(0); MMA(1, 0, At, B0); MMA(1, 1, At, B1); BAR; }
;   { LDB(B0, 1, 0); LDA(At, 1, 0); WAIT_V(2); BAR; WAIT_L(0); MMA(0, 0, At, B0); BAR;
;     LDB(B1, 1, 1); WAIT_V(0); BAR; WAIT_L(0); MMA(0, 1, At, B1); BAR;
;     LDA(At, 1, 1); BAR; WAIT_L(0); MMA(1, 0, At, B0); MMA(1, 1, At, B1); BAR; }
	v_mfma_f32_16x16x32_bf16 v[76:79], v[224:227], v[208:211], v[76:79]
	v_mfma_f32_16x16x32_bf16 v[80:83], v[232:235], v[208:211], v[80:83]
	v_mfma_f32_16x16x32_bf16 v[88:91], v[224:227], v[216:219], v[88:91]
	v_mfma_f32_16x16x32_bf16 v[92:95], v[232:235], v[216:219], v[92:95]
	s_setprio 0
	ds_read_b128 v[144:147], v149
	ds_read_b128 v[156:159], v149 offset:1024
	ds_read_b128 v[180:183], v149 offset:256
	ds_read_b128 v[184:187], v149 offset:1280
	s_mov_b32 m0, s41
	ds_read_b128 v[140:143], v128 offset:32768
	ds_read_b128 v[188:191], v128 offset:33792
	ds_read_b128 v[192:195], v153 offset:32768
	ds_read_b128 v[196:199], v153 offset:33792
	ds_read_b128 v[200:203], v154 offset:32768
	ds_read_b128 v[204:207], v154 offset:33792
	ds_read_b128 v[208:211], v155 offset:32768
	ds_read_b128 v[212:215], v155 offset:33792
	global_load_lds_dwordx4 v[236:237], off
	s_mov_b32 m0, vcc_lo
	v_lshl_add_u64 v[132:133], v[236:237], 0, s[8:9]
	global_load_lds_dwordx4 v[238:239], off
	v_lshl_add_u64 v[134:135], v[238:239], 0, s[8:9]
	s_waitcnt lgkmcnt(8)
	s_barrier
	s_waitcnt lgkmcnt(0)
	s_setprio 1
	s_waitcnt lgkmcnt(0)
	v_mfma_f32_16x16x32_bf16 v[124:127], v[144:147], v[140:143], v[124:127]
	v_mfma_f32_16x16x32_bf16 v[120:123], v[180:183], v[140:143], v[120:123]
	v_mfma_f32_16x16x32_bf16 v[116:119], v[144:147], v[192:195], v[116:119]
	v_mfma_f32_16x16x32_bf16 v[112:115], v[180:183], v[192:195], v[112:115]
	v_mfma_f32_16x16x32_bf16 v[108:111], v[144:147], v[200:203], v[108:111]
	v_mfma_f32_16x16x32_bf16 v[104:107], v[180:183], v[200:203], v[104:107]
	v_mfma_f32_16x16x32_bf16 v[100:103], v[144:147], v[208:211], v[100:103]
	v_mfma_f32_16x16x32_bf16 v[96:99], v[180:183], v[208:211], v[96:99]
	v_mfma_f32_16x16x32_bf16 v[124:127], v[156:159], v[188:191], v[124:127]
	v_mfma_f32_16x16x32_bf16 v[120:123], v[184:187], v[188:191], v[120:123]
	v_mfma_f32_16x16x32_bf16 v[116:119], v[156:159], v[196:199], v[116:119]
	v_mfma_f32_16x16x32_bf16 v[112:115], v[184:187], v[196:199], v[112:115]
	s_barrier
	v_mfma_f32_16x16x32_bf16 v[108:111], v[156:159], v[204:207], v[108:111]
	v_mfma_f32_16x16x32_bf16 v[104:107], v[184:187], v[204:207], v[104:107]
	v_mfma_f32_16x16x32_bf16 v[100:103], v[156:159], v[212:215], v[100:103]
	v_mfma_f32_16x16x32_bf16 v[96:99], v[184:187], v[212:215], v[96:99]
	s_setprio 0
	s_mov_b32 m0, vcc_hi
	ds_read_b128 v[216:219], v148
	ds_read_b128 v[220:223], v148 offset:1024
	ds_read_b128 v[224:227], v148 offset:256
	ds_read_b128 v[228:231], v148 offset:1280
	global_load_lds_dwordx4 v[240:241], off
	s_mov_b32 m0, s28
	v_lshl_add_u64 v[136:137], v[240:241], 0, s[8:9]
	global_load_lds_dwordx4 v[242:243], off
	v_lshl_add_u64 v[138:139], v[242:243], 0, s[8:9]
	s_barrier
	s_waitcnt lgkmcnt(0)
	s_setprio 1
	s_waitcnt lgkmcnt(0)
	v_mfma_f32_16x16x32_bf16 v[84:87], v[216:219], v[140:143], v[84:87]
	v_mfma_f32_16x16x32_bf16 v[68:71], v[224:227], v[140:143], v[68:71]
	v_mfma_f32_16x16x32_bf16 v[52:55], v[216:219], v[192:195], v[52:55]
	v_mfma_f32_16x16x32_bf16 v[48:51], v[224:227], v[192:195], v[48:51]
	v_mfma_f32_16x16x32_bf16 v[44:47], v[216:219], v[200:203], v[44:47]
	v_mfma_f32_16x16x32_bf16 v[40:43], v[224:227], v[200:203], v[40:43]
	v_mfma_f32_16x16x32_bf16 v[36:39], v[216:219], v[208:211], v[36:39]
	v_mfma_f32_16x16x32_bf16 v[32:35], v[224:227], v[208:211], v[32:35]
	v_mfma_f32_16x16x32_bf16 v[84:87], v[220:223], v[188:191], v[84:87]
	v_mfma_f32_16x16x32_bf16 v[68:71], v[228:231], v[188:191], v[68:71]
	v_mfma_f32_16x16x32_bf16 v[52:55], v[220:223], v[196:199], v[52:55]
	v_mfma_f32_16x16x32_bf16 v[48:51], v[228:231], v[196:199], v[48:51]
	s_barrier
	v_mfma_f32_16x16x32_bf16 v[44:47], v[220:223], v[204:207], v[44:47]
	v_mfma_f32_16x16x32_bf16 v[40:43], v[228:231], v[204:207], v[40:43]
	v_mfma_f32_16x16x32_bf16 v[36:39], v[220:223], v[212:215], v[36:39]
	v_mfma_f32_16x16x32_bf16 v[32:35], v[228:231], v[212:215], v[32:35]
	s_setprio 0
	s_mov_b32 m0, s94
	ds_read_b128 v[188:191], v128 offset:49152
	ds_read_b128 v[192:195], v128 offset:50176
	ds_read_b128 v[196:199], v153 offset:49152
	ds_read_b128 v[200:203], v153 offset:50176
	ds_read_b128 v[204:207], v154 offset:49152
	ds_read_b128 v[208:211], v154 offset:50176
	ds_read_b128 v[212:215], v155 offset:49152
	ds_read_b128 v[232:235], v155 offset:50176
	global_load_lds_dwordx4 v[244:245], off
	s_mov_b32 m0, s95
	v_lshl_add_u64 v[140:141], v[244:245], 0, s[8:9]
	global_load_lds_dwordx4 v[246:247], off
	v_lshl_add_u64 v[142:143], v[246:247], 0, s[8:9]
	s_barrier
	s_waitcnt lgkmcnt(0)
	s_setprio 1
	s_waitcnt lgkmcnt(0)
	v_mfma_f32_16x16x32_bf16 v[28:31], v[144:147], v[188:191], v[28:31]
	v_mfma_f32_16x16x32_bf16 v[24:27], v[180:183], v[188:191], v[24:27]
	v_mfma_f32_16x16x32_bf16 v[20:23], v[144:147], v[196:199], v[20:23]
	v_mfma_f32_16x16x32_bf16 v[16:19], v[180:183], v[196:199], v[16:19]
	v_mfma_f32_16x16x32_bf16 v[12:15], v[144:147], v[204:207], v[12:15]
	v_mfma_f32_16x16x32_bf16 v[8:11], v[180:183], v[204:207], v[8:11]
	v_mfma_f32_16x16x32_bf16 v[4:7], v[144:147], v[212:215], v[4:7]
	v_mfma_f32_16x16x32_bf16 v[0:3], v[180:183], v[212:215], v[0:3]
	v_mfma_f32_16x16x32_bf16 v[28:31], v[156:159], v[192:195], v[28:31]
	v_mfma_f32_16x16x32_bf16 v[24:27], v[184:187], v[192:195], v[24:27]
	v_mfma_f32_16x16x32_bf16 v[20:23], v[156:159], v[200:203], v[20:23]
	v_mfma_f32_16x16x32_bf16 v[16:19], v[184:187], v[200:203], v[16:19]
	s_barrier
	v_mfma_f32_16x16x32_bf16 v[12:15], v[156:159], v[208:211], v[12:15]
	v_mfma_f32_16x16x32_bf16 v[8:11], v[184:187], v[208:211], v[8:11]
	v_mfma_f32_16x16x32_bf16 v[4:7], v[156:159], v[232:235], v[4:7]
	v_mfma_f32_16x16x32_bf16 v[0:3], v[184:187], v[232:235], v[0:3]
	s_setprio 0
	s_mov_b32 m0, s62
	v_lshl_add_u64 v[144:145], v[248:249], 0, s[8:9]
	global_load_lds_dwordx4 v[248:249], off
	s_mov_b32 m0, s63
	v_lshl_add_u64 v[146:147], v[250:251], 0, s[8:9]
	global_load_lds_dwordx4 v[250:251], off
	s_waitcnt vmcnt(6)
	s_barrier
	s_setprio 1
	v_mfma_f32_16x16x32_bf16 v[56:59], v[216:219], v[188:191], v[56:59]
	v_mfma_f32_16x16x32_bf16 v[60:63], v[224:227], v[188:191], v[60:63]
	v_mfma_f32_16x16x32_bf16 v[64:67], v[216:219], v[196:199], v[64:67]
	v_mfma_f32_16x16x32_bf16 v[72:75], v[224:227], v[196:199], v[72:75]
	v_mfma_f32_16x16x32_bf16 v[76:79], v[216:219], v[204:207], v[76:79]
	v_mfma_f32_16x16x32_bf16 v[80:83], v[224:227], v[204:207], v[80:83]
	v_mfma_f32_16x16x32_bf16 v[88:91], v[216:219], v[212:215], v[88:91]
	v_mfma_f32_16x16x32_bf16 v[92:95], v[224:227], v[212:215], v[92:95]
	v_mfma_f32_16x16x32_bf16 v[56:59], v[220:223], v[192:195], v[56:59]
	v_mfma_f32_16x16x32_bf16 v[60:63], v[228:231], v[192:195], v[60:63]
	v_mfma_f32_16x16x32_bf16 v[64:67], v[220:223], v[200:203], v[64:67]
	v_mfma_f32_16x16x32_bf16 v[72:75], v[228:231], v[200:203], v[72:75]
	s_barrier
	v_mfma_f32_16x16x32_bf16 v[76:79], v[220:223], v[208:211], v[76:79]
	v_mfma_f32_16x16x32_bf16 v[80:83], v[228:231], v[208:211], v[80:83]
	v_mfma_f32_16x16x32_bf16 v[88:91], v[220:223], v[232:235], v[88:91]
	v_mfma_f32_16x16x32_bf16 v[92:95], v[228:231], v[232:235], v[92:95]
	s_setprio 0
	s_mov_b32 s63, 1

; #define STAGE(P, q) do { GLDS16(q[0], (unsigned char*)(P) + wid * 1024); GLDS16(q[1], (unsigned char*)(P) + wid * 1024 + 8192); \
;     q[0] += 128; q[1] += 128; asm volatile("" : "+v"(q[0]), "+v"(q[1])); } while (0)
; #define LDA(dst, b, h) _Pragma("unroll") for (int m = 0; m < 4; ++m) _Pragma("unroll") for (int k = 0; k < 2; ++k) \
;     dst[m][k] = *(const bf16x8*)((const unsigned char*)SA(b, h) + lds_byte1(wr * 64 + m * 16 + fr, k * 32 + fq * 8))
; #define LDB(dst, b, h) _Pragma("unroll") for (int n = 0; n < 2; ++n) _Pragma("unroll") for (int k = 0; k < 2; ++k) \
;     dst[n][k] = *(const bf16x8*)((const unsigned char*)SB(b, h) + lds_byte1(wc * 32 + n * 16 + fr, k * 32 + fq * 8))
; #define MMA(ai, bj, At_, Bt_) do { __builtin_amdgcn_s_setprio(1); \
;     _Pragma("unroll") for (int m = 0; m < 4; ++m) _Pragma("unroll") for (int n = 0; n < 2; ++n) _Pragma("unroll") for (int k = 0; k < 2; ++k) \
;       acc[ai][bj][m][n] = mfma16(At_[m][k], Bt_[n][k], acc[ai][bj][m][n]); \
;     __builtin_amdgcn_s_setprio(0); } while (0)
; #define WAIT_V(n) asm volatile("s_waitcnt vmcnt(" #n ")" ::: "memory")
; #define WAIT_L(n) asm volatile("s_waitcnt lgkmcnt(" #n ")" ::: "memory")
; #define BAR __builtin_amdgcn_s_barrier()
; #define SCHED __builtin_amdgcn_sched_barrier(0)
; DEV void gemm_tile(const u16* __restrict__ A, const u16* __restrict__ Bt, u16* __restrict__ C, int N, int K,
;                    int brow, int bcol, unsigned char* smem, int epi, const GateEpi& ge) {
;     ...
; #pragma unroll
;   for (int a = 0; a < 2; ++a)
; #pragma unroll
;     for (int b = 0; b < 2; ++b)
; #pragma unroll
;       for (int m = 0; m < 4; ++m)
; #pragma unroll
;         for (int n = 0; n < 2; ++n) acc[a][b][m][n] = (f32x4){0.f, 0.f, 0.f, 0.f};
;     ...
;   for (int t = 0; t < nt - 2; t += 2) {
;     LDB(B0, 0, 0); SCHED; LDA(At, 0, 0); STAGE(SA(1, 1), qA1);
;     WAIT_L(8); BAR; WAIT_L(0); MMA(0, 0, At, B0); BAR; SCHED;
;     LDB(B1, 0, 1); STAGE(SB(0, 0), qB0);
;     BAR; WAIT_L(0); MMA(0, 1, At, B1); BAR;
;     LDA(At, 0, 1); STAGE(SA(0, 0), qA0);
;     BAR; WAIT_L(0); MMA(1, 0, At, B0); BAR; SCHED;
;     STAGE(SB(0, 1), qB1);
;     WAIT_V(6); BAR; MMA(1, 1, At, B1); BAR;
.Lg_nostag:
	ds_read_b128 v[156:159], v152
	ds_read_b128 v[180:183], v152 offset:1024
	ds_read_b128 v[184:187], v152 offset:256
	ds_read_b128 v[188:191], v152 offset:1280
	s_mov_b32 m0, s56
	v_add_u32_e32 v153, s53, v151
	v_add_u32_e32 v154, s54, v151
	v_add_u32_e32 v155, s55, v151
	ds_read_b128 v[192:195], v128
	ds_read_b128 v[196:199], v128 offset:1024
	ds_read_b128 v[200:203], v153
	ds_read_b128 v[204:207], v153 offset:1024
	ds_read_b128 v[208:211], v154
	ds_read_b128 v[212:215], v154 offset:1024
	ds_read_b128 v[216:219], v155
	ds_read_b128 v[220:223], v155 offset:1024
	global_load_lds_dwordx4 v[132:133], off
	s_mov_b32 m0, s52
	v_lshl_add_u64 v[236:237], v[132:133], 0, s[8:9]
	global_load_lds_dwordx4 v[134:135], off
	v_lshl_add_u64 v[238:239], v[134:135], 0, s[8:9]
	s_waitcnt lgkmcnt(8)
	s_barrier
	s_waitcnt lgkmcnt(0)
	s_setprio 1
	s_waitcnt lgkmcnt(0)
	v_mfma_f32_16x16x32_bf16 v[124:127], v[156:159], v[192:195], 0
	v_mfma_f32_16x16x32_bf16 v[120:123], v[184:187], v[192:195], 0
	v_mfma_f32_16x16x32_bf16 v[116:119], v[156:159], v[200:203], 0
	v_mfma_f32_16x16x32_bf16 v[112:115], v[184:187], v[200:203], 0
	v_mfma_f32_16x16x32_bf16 v[108:111], v[156:159], v[208:211], 0
	v_mfma_f32_16x16x32_bf16 v[104:107], v[184:187], v[208:211], 0
	v_mfma_f32_16x16x32_bf16 v[100:103], v[156:159], v[216:219], 0
	v_mfma_f32_16x16x32_bf16 v[96:99], v[184:187], v[216:219], 0
	v_mfma_f32_16x16x32_bf16 v[124:127], v[180:183], v[196:199], v[124:127]
	v_mfma_f32_16x16x32_bf16 v[120:123], v[188:191], v[196:199], v[120:123]
	v_mfma_f32_16x16x32_bf16 v[116:119], v[180:183], v[204:207], v[116:119]
	v_mfma_f32_16x16x32_bf16 v[112:115], v[188:191], v[204:207], v[112:115]
	s_barrier
	v_mfma_f32_16x16x32_bf16 v[108:111], v[180:183], v[212:215], v[108:111]
	v_mfma_f32_16x16x32_bf16 v[104:107], v[188:191], v[212:215], v[104:107]
	v_mfma_f32_16x16x32_bf16 v[100:103], v[180:183], v[220:223], v[100:103]
	v_mfma_f32_16x16x32_bf16 v[96:99], v[188:191], v[220:223], v[96:99]
	s_setprio 0
	s_mov_b32 m0, s4
	ds_read_b128 v[132:135], v150
	ds_read_b128 v[224:227], v150 offset:1024
	ds_read_b128 v[228:231], v150 offset:256
	ds_read_b128 v[232:235], v150 offset:1280
	global_load_lds_dwordx4 v[136:137], off
	s_mov_b32 m0, s5
	v_lshl_add_u64 v[240:241], v[136:137], 0, s[8:9]
	global_load_lds_dwordx4 v[138:139], off
	v_lshl_add_u64 v[242:243], v[138:139], 0, s[8:9]
	s_barrier
	s_waitcnt lgkmcnt(0)
	s_setprio 1
	s_waitcnt lgkmcnt(0)
	v_mfma_f32_16x16x32_bf16 v[84:87], v[132:135], v[192:195], 0
	v_mfma_f32_16x16x32_bf16 v[68:71], v[228:231], v[192:195], 0
	v_mfma_f32_16x16x32_bf16 v[52:55], v[132:135], v[200:203], 0
	v_mfma_f32_16x16x32_bf16 v[48:51], v[228:231], v[200:203], 0
	v_mfma_f32_16x16x32_bf16 v[44:47], v[132:135], v[208:211], 0
	v_mfma_f32_16x16x32_bf16 v[40:43], v[228:231], v[208:211], 0
	v_mfma_f32_16x16x32_bf16 v[36:39], v[132:135], v[216:219], 0
	v_mfma_f32_16x16x32_bf16 v[32:35], v[228:231], v[216:219], 0
	v_mfma_f32_16x16x32_bf16 v[84:87], v[224:227], v[196:199], v[84:87]
	v_mfma_f32_16x16x32_bf16 v[68:71], v[232:235], v[196:199], v[68:71]
	v_mfma_f32_16x16x32_bf16 v[52:55], v[224:227], v[204:207], v[52:55]
	v_mfma_f32_16x16x32_bf16 v[48:51], v[232:235], v[204:207], v[48:51]
	s_barrier
	v_mfma_f32_16x16x32_bf16 v[44:47], v[224:227], v[212:215], v[44:47]
	v_mfma_f32_16x16x32_bf16 v[40:43], v[232:235], v[212:215], v[40:43]
	v_mfma_f32_16x16x32_bf16 v[36:39], v[224:227], v[220:223], v[36:39]
	v_mfma_f32_16x16x32_bf16 v[32:35], v[232:235], v[220:223], v[32:35]
	s_setprio 0
	s_mov_b32 m0, s1
	ds_read_b128 v[136:139], v128 offset:16384
	ds_read_b128 v[192:195], v128 offset:17408
	ds_read_b128 v[196:199], v153 offset:16384
	ds_read_b128 v[200:203], v153 offset:17408
	ds_read_b128 v[204:207], v154 offset:16384
	ds_read_b128 v[208:211], v154 offset:17408
	ds_read_b128 v[212:215], v155 offset:16384
	ds_read_b128 v[216:219], v155 offset:17408
	global_load_lds_dwordx4 v[140:141], off
	s_mov_b32 m0, s6
	v_lshl_add_u64 v[244:245], v[140:141], 0, s[8:9]
	global_load_lds_dwordx4 v[142:143], off
	v_lshl_add_u64 v[246:247], v[142:143], 0, s[8:9]
	s_barrier
	s_waitcnt lgkmcnt(0)
	s_setprio 1
	s_waitcnt lgkmcnt(0)
	v_mfma_f32_16x16x32_bf16 v[28:31], v[156:159], v[136:139], 0
	v_mfma_f32_16x16x32_bf16 v[24:27], v[184:187], v[136:139], 0
	v_mfma_f32_16x16x32_bf16 v[20:23], v[156:159], v[196:199], 0
	v_mfma_f32_16x16x32_bf16 v[16:19], v[184:187], v[196:199], 0
	v_mfma_f32_16x16x32_bf16 v[12:15], v[156:159], v[204:207], 0
	v_mfma_f32_16x16x32_bf16 v[8:11], v[184:187], v[204:207], 0
	v_mfma_f32_16x16x32_bf16 v[4:7], v[156:159], v[212:215], 0
	v_mfma_f32_16x16x32_bf16 v[0:3], v[184:187], v[212:215], 0
	v_mfma_f32_16x16x32_bf16 v[28:31], v[180:183], v[192:195], v[28:31]
	v_mfma_f32_16x16x32_bf16 v[24:27], v[188:191], v[192:195], v[24:27]
	v_mfma_f32_16x16x32_bf16 v[20:23], v[180:183], v[200:203], v[20:23]
	v_mfma_f32_16x16x32_bf16 v[16:19], v[188:191], v[200:203], v[16:19]
	s_barrier
	v_mfma_f32_16x16x32_bf16 v[12:15], v[180:183], v[208:211], v[12:15]
	v_mfma_f32_16x16x32_bf16 v[8:11], v[188:191], v[208:211], v[8:11]
	v_mfma_f32_16x16x32_bf16 v[4:7], v[180:183], v[216:219], v[4:7]
	v_mfma_f32_16x16x32_bf16 v[0:3], v[188:191], v[216:219], v[0:3]
	s_setprio 0
	s_mov_b32 m0, s7
	v_lshl_add_u64 v[248:249], v[144:145], 0, s[8:9]
	global_load_lds_dwordx4 v[144:145], off
	s_mov_b32 m0, s35
	v_lshl_add_u64 v[250:251], v[146:147], 0, s[8:9]
	global_load_lds_dwordx4 v[146:147], off
	s_waitcnt vmcnt(6)
	s_barrier
; #define STAGE(P, q) do { GLDS16(q[0], (unsigned char*)(P) + wid * 1024); GLDS16(q[1], (unsigned char*)(P) + wid * 1024 + 8192); \
;     q[0] += 128; q[1] += 128; asm volatile("" : "+v"(q[0]), "+v"(q[1])); } while (0)
; #define LDA(dst, b, h) _Pragma("unroll") for (int m = 0; m < 4; ++m) _Pragma("unroll") for (int k = 0; k < 2; ++k) \
;     dst[m][k] = *(const bf16x8*)((const unsigned char*)SA(b, h) + lds_byte1(wr * 64 + m * 16 + fr, k * 32 + fq * 8))
; #define LDB(dst, b, h) _Pragma("unroll") for (int n = 0; n < 2; ++n) _Pragma("unroll") for (int k = 0; k < 2; ++k) \
;     dst[n][k] = *(const bf16x8*)((const unsigned char*)SB(b, h) + lds_byte1(wc * 32 + n * 16 + fr, k * 32 + fq * 8))
; #define MMA(ai, bj, At_, Bt_) do { __builtin_amdgcn_s_setprio(1); \
;     _Pragma("unroll") for (int m = 0; m < 4; ++m) _Pragma("unroll") for (int n = 0; n < 2; ++n) _Pragma("unroll") for (int k = 0; k < 2; ++k) \
;       acc[ai][bj][m][n] = mfma16(At_[m][k], Bt_[n][k], acc[ai][bj][m][n]); \
;     __builtin_amdgcn_s_setprio(0); } while (0)
; #define WAIT_V(n) asm volatile("s_waitcnt vmcnt(" #n ")" ::: "memory")
; #define WAIT_L(n) asm volatile("s_waitcnt lgkmcnt(" #n ")" ::: "memory")
; #define BAR __builtin_amdgcn_s_barrier()
; #define SCHED __builtin_amdgcn_sched_barrier(0)
; DEV void gemm_tile(const u16* __restrict__ A, const u16* __restrict__ Bt, u16* __restrict__ C, int N, int K,
;                    int brow, int bcol, unsigned char* smem, int epi, const GateEpi& ge) {
;     ...
;     BAR; WAIT_L(0); MMA(0, 1, At, B1); BAR;
;     LDA(At, 0, 1); STAGE(SA(0, 0), qA0);
;     BAR; WAIT_L(0); MMA(1, 0, At, B0); BAR; SCHED;
;     STAGE(SB(0, 1), qB1);
;     WAIT_V(6); BAR; MMA(1, 1, At, B1); BAR;
;     LDB(B0, 1, 0); SCHED; LDA(At, 1, 0); STAGE(SA(0, 1), qA1);
;     WAIT_L(8); BAR; WAIT_L(0); MMA(0, 0, At, B0); BAR; SCHED;
	s_setprio 1
	v_mfma_f32_16x16x32_bf16 v[56:59], v[132:135], v[136:139], 0
	v_mfma_f32_16x16x32_bf16 v[60:63], v[228:231], v[136:139], 0
	v_mfma_f32_16x16x32_bf16 v[64:67], v[132:135], v[196:199], 0
	v_mfma_f32_16x16x32_bf16 v[72:75], v[228:231], v[196:199], 0
	v_mfma_f32_16x16x32_bf16 v[76:79], v[132:135], v[204:207], 0
	v_mfma_f32_16x16x32_bf16 v[80:83], v[228:231], v[204:207], 0
	v_mfma_f32_16x16x32_bf16 v[88:91], v[132:135], v[212:215], 0
	v_mfma_f32_16x16x32_bf16 v[92:95], v[228:231], v[212:215], 0
	v_mfma_f32_16x16x32_bf16 v[56:59], v[224:227], v[192:195], v[56:59]
	v_mfma_f32_16x16x32_bf16 v[60:63], v[232:235], v[192:195], v[60:63]
	v_mfma_f32_16x16x32_bf16 v[64:67], v[224:227], v[200:203], v[64:67]
	v_mfma_f32_16x16x32_bf16 v[72:75], v[232:235], v[200:203], v[72:75]
	s_barrier
	v_mfma_f32_16x16x32_bf16 v[76:79], v[224:227], v[208:211], v[76:79]
	v_mfma_f32_16x16x32_bf16 v[80:83], v[232:235], v[208:211], v[80:83]
	v_mfma_f32_16x16x32_bf16 v[88:91], v[224:227], v[216:219], v[88:91]
	v_mfma_f32_16x16x32_bf16 v[92:95], v[232:235], v[216:219], v[92:95]
	s_setprio 0
	ds_read_b128 v[144:147], v149
	ds_read_b128 v[156:159], v149 offset:1024
	ds_read_b128 v[180:183], v149 offset:256
	ds_read_b128 v[184:187], v149 offset:1280
	s_mov_b32 m0, s41
	ds_read_b128 v[140:143], v128 offset:32768
	ds_read_b128 v[188:191], v128 offset:33792
	ds_read_b128 v[192:195], v153 offset:32768
	ds_read_b128 v[196:199], v153 offset:33792
	ds_read_b128 v[200:203], v154 offset:32768
	ds_read_b128 v[204:207], v154 offset:33792
	ds_read_b128 v[208:211], v155 offset:32768
	ds_read_b128 v[212:215], v155 offset:33792
	global_load_lds_dwordx4 v[236:237], off
	s_mov_b32 m0, vcc_lo
	v_lshl_add_u64 v[132:133], v[236:237], 0, s[8:9]
	global_load_lds_dwordx4 v[238:239], off
	v_lshl_add_u64 v[134:135], v[238:239], 0, s[8:9]
	s_waitcnt lgkmcnt(8)
	s_barrier
	s_waitcnt lgkmcnt(0)
	s_setprio 1
	s_waitcnt lgkmcnt(0)
	v_mfma_f32_16x16x32_bf16 v[124:127], v[144:147], v[140:143], v[124:127]
	v_mfma_f32_16x16x32_bf16 v[120:123], v[180:183], v[140:143], v[120:123]
	v_mfma_f32_16x16x32_bf16 v[116:119], v[144:147], v[192:195], v[116:119]
	v_mfma_f32_16x16x32_bf16 v[112:115], v[180:183], v[192:195], v[112:115]
	v_mfma_f32_16x16x32_bf16 v[108:111], v[144:147], v[200:203], v[108:111]
	v_mfma_f32_16x16x32_bf16 v[104:107], v[180:183], v[200:203], v[104:107]
	v_mfma_f32_16x16x32_bf16 v[100:103], v[144:147], v[208:211], v[100:103]
	v_mfma_f32_16x16x32_bf16 v[96:99], v[180:183], v[208:211], v[96:99]
	v_mfma_f32_16x16x32_bf16 v[124:127], v[156:159], v[188:191], v[124:127]
	v_mfma_f32_16x16x32_bf16 v[120:123], v[184:187], v[188:191], v[120:123]
	v_mfma_f32_16x16x32_bf16 v[116:119], v[156:159], v[196:199], v[116:119]
	v_mfma_f32_16x16x32_bf16 v[112:115], v[184:187], v[196:199], v[112:115]
	s_barrier
	v_mfma_f32_16x16x32_bf16 v[108:111], v[156:159], v[204:207], v[108:111]
	v_mfma_f32_16x16x32_bf16 v[104:107], v[184:187], v[204:207], v[104:107]
	v_mfma_f32_16x16x32_bf16 v[100:103], v[156:159], v[212:215], v[100:103]
	v_mfma_f32_16x16x32_bf16 v[96:99], v[184:187], v[212:215], v[96:99]
	s_setprio 0
	s_mov_b32 m0, vcc_hi
	ds_read_b128 v[216:219], v148
	ds_read_b128 v[220:223], v148 offset:1024
	ds_read_b128 v[224:227], v148 offset:256
	ds_read_b128 v[228:231], v148 offset:1280
	global_load_lds_dwordx4 v[240:241], off
	s_mov_b32 m0, s28
	v_lshl_add_u64 v[136:137], v[240:241], 0, s[8:9]
	global_load_lds_dwordx4 v[242:243], off
	v_lshl_add_u64 v[138:139], v[242:243], 0, s[8:9]
	s_barrier
; #define STAGE(P, q) do { GLDS16(q[0], (unsigned char*)(P) + wid * 1024); GLDS16(q[1], (unsigned char*)(P) + wid * 1024 + 8192); \
;     q[0] += 128; q[1] += 128; asm volatile("" : "+v"(q[0]), "+v"(q[1])); } while (0)
; #define LDA(dst, b, h) _Pragma("unroll") for (int m = 0; m < 4; ++m) _Pragma("unroll") for (int k = 0; k < 2; ++k) \
;     dst[m][k] = *(const bf16x8*)((const unsigned char*)SA(b, h) + lds_byte1(wr * 64 + m * 16 + fr, k * 32 + fq * 8))
; #define LDB(dst, b, h) _Pragma("unroll") for (int n = 0; n < 2; ++n) _Pragma("unroll") for (int k = 0; k < 2; ++k) \
;     dst[n][k] = *(const bf16x8*)((const unsigned char*)SB(b, h) + lds_byte1(wc * 32 + n * 16 + fr, k * 32 + fq * 8))
; #define MMA(ai, bj, At_, Bt_) do { __builtin_amdgcn_s_setprio(1); \
;     _Pragma("unroll") for (int m = 0; m < 4; ++m) _Pragma("unroll") for (int n = 0; n < 2; ++n) _Pragma("unroll") for (int k = 0; k < 2; ++k) \
;       acc[ai][bj][m][n] = mfma16(At_[m][k], Bt_[n][k], acc[ai][bj][m][n]); \
;     __builtin_amdgcn_s_setprio(0); } while (0)
; #define WAIT_V(n) asm volatile("s_waitcnt vmcnt(" #n ")" ::: "memory")
; #define WAIT_L(n) asm volatile("s_waitcnt lgkmcnt(" #n ")" ::: "memory")
; #define BAR __builtin_amdgcn_s_barrier()
; #define SCHED __builtin_amdgcn_sched_barrier(0)
; DEV void gemm_tile(const u16* __restrict__ A, const u16* __restrict__ Bt, u16* __restrict__ C, int N, int K,
;                    int brow, int bcol, unsigned char* smem, int epi, const GateEpi& ge) {
;     ...
;     WAIT_L(8); BAR; WAIT_L(0); MMA(0, 0, At, B0); BAR; SCHED;
;     LDB(B1, 1, 1); STAGE(SB(1, 0), qB0);
;     BAR; WAIT_L(0); MMA(0, 1, At, B1); BAR;
;     LDA(At, 1, 1); STAGE(SA(1, 0), qA0);
;     BAR; WAIT_L(0); MMA(1, 0, At, B0); BAR; SCHED;
;     STAGE(SB(1, 1), qB1);
;     WAIT_V(6); BAR; MMA(1, 1, At, B1); BAR;
	s_waitcnt lgkmcnt(0)
	s_setprio 1
	s_waitcnt lgkmcnt(0)
	v_mfma_f32_16x16x32_bf16 v[84:87], v[216:219], v[140:143], v[84:87]
	v_mfma_f32_16x16x32_bf16 v[68:71], v[224:227], v[140:143], v[68:71]
	v_mfma_f32_16x16x32_bf16 v[52:55], v[216:219], v[192:195], v[52:55]
	v_mfma_f32_16x16x32_bf16 v[48:51], v[224:227], v[192:195], v[48:51]
	v_mfma_f32_16x16x32_bf16 v[44:47], v[216:219], v[200:203], v[44:47]
	v_mfma_f32_16x16x32_bf16 v[40:43], v[224:227], v[200:203], v[40:43]
	v_mfma_f32_16x16x32_bf16 v[36:39], v[216:219], v[208:211], v[36:39]
	v_mfma_f32_16x16x32_bf16 v[32:35], v[224:227], v[208:211], v[32:35]
	v_mfma_f32_16x16x32_bf16 v[84:87], v[220:223], v[188:191], v[84:87]
	v_mfma_f32_16x16x32_bf16 v[68:71], v[228:231], v[188:191], v[68:71]
	v_mfma_f32_16x16x32_bf16 v[52:55], v[220:223], v[196:199], v[52:55]
	v_mfma_f32_16x16x32_bf16 v[48:51], v[228:231], v[196:199], v[48:51]
	s_barrier
	v_mfma_f32_16x16x32_bf16 v[44:47], v[220:223], v[204:207], v[44:47]
	v_mfma_f32_16x16x32_bf16 v[40:43], v[228:231], v[204:207], v[40:43]
	v_mfma_f32_16x16x32_bf16 v[36:39], v[220:223], v[212:215], v[36:39]
	v_mfma_f32_16x16x32_bf16 v[32:35], v[228:231], v[212:215], v[32:35]
	s_setprio 0
	s_mov_b32 m0, s94
	ds_read_b128 v[188:191], v128 offset:49152
	ds_read_b128 v[192:195], v128 offset:50176
	ds_read_b128 v[196:199], v153 offset:49152
	ds_read_b128 v[200:203], v153 offset:50176
	ds_read_b128 v[204:207], v154 offset:49152
	ds_read_b128 v[208:211], v154 offset:50176
	ds_read_b128 v[212:215], v155 offset:49152
	ds_read_b128 v[232:235], v155 offset:50176
	global_load_lds_dwordx4 v[244:245], off
	s_mov_b32 m0, s95
	v_lshl_add_u64 v[140:141], v[244:245], 0, s[8:9]
	global_load_lds_dwordx4 v[246:247], off
	v_lshl_add_u64 v[142:143], v[246:247], 0, s[8:9]
	s_barrier
	s_waitcnt lgkmcnt(0)
	s_setprio 1
	s_waitcnt lgkmcnt(0)
	v_mfma_f32_16x16x32_bf16 v[28:31], v[144:147], v[188:191], v[28:31]
	v_mfma_f32_16x16x32_bf16 v[24:27], v[180:183], v[188:191], v[24:27]
	v_mfma_f32_16x16x32_bf16 v[20:23], v[144:147], v[196:199], v[20:23]
	v_mfma_f32_16x16x32_bf16 v[16:19], v[180:183], v[196:199], v[16:19]
	v_mfma_f32_16x16x32_bf16 v[12:15], v[144:147], v[204:207], v[12:15]
	v_mfma_f32_16x16x32_bf16 v[8:11], v[180:183], v[204:207], v[8:11]
	v_mfma_f32_16x16x32_bf16 v[4:7], v[144:147], v[212:215], v[4:7]
	v_mfma_f32_16x16x32_bf16 v[0:3], v[180:183], v[212:215], v[0:3]
	v_mfma_f32_16x16x32_bf16 v[28:31], v[156:159], v[192:195], v[28:31]
	v_mfma_f32_16x16x32_bf16 v[24:27], v[184:187], v[192:195], v[24:27]
	v_mfma_f32_16x16x32_bf16 v[20:23], v[156:159], v[200:203], v[20:23]
	v_mfma_f32_16x16x32_bf16 v[16:19], v[184:187], v[200:203], v[16:19]
	s_barrier
	v_mfma_f32_16x16x32_bf16 v[12:15], v[156:159], v[208:211], v[12:15]
	v_mfma_f32_16x16x32_bf16 v[8:11], v[184:187], v[208:211], v[8:11]
	v_mfma_f32_16x16x32_bf16 v[4:7], v[156:159], v[232:235], v[4:7]
	v_mfma_f32_16x16x32_bf16 v[0:3], v[184:187], v[232:235], v[0:3]
	s_setprio 0
	s_mov_b32 m0, s62
	v_lshl_add_u64 v[144:145], v[248:249], 0, s[8:9]
	global_load_lds_dwordx4 v[248:249], off
	s_mov_b32 m0, s63
	v_lshl_add_u64 v[146:147], v[250:251], 0, s[8:9]
	global_load_lds_dwordx4 v[250:251], off
	s_waitcnt vmcnt(6)
	s_barrier
	s_setprio 1
	v_mfma_f32_16x16x32_bf16 v[56:59], v[216:219], v[188:191], v[56:59]
	v_mfma_f32_16x16x32_bf16 v[60:63], v[224:227], v[188:191], v[60:63]
	v_mfma_f32_16x16x32_bf16 v[64:67], v[216:219], v[196:199], v[64:67]
	v_mfma_f32_16x16x32_bf16 v[72:75], v[224:227], v[196:199], v[72:75]
	v_mfma_f32_16x16x32_bf16 v[76:79], v[216:219], v[204:207], v[76:79]
	v_mfma_f32_16x16x32_bf16 v[80:83], v[224:227], v[204:207], v[80:83]
	v_mfma_f32_16x16x32_bf16 v[88:91], v[216:219], v[212:215], v[88:91]
	v_mfma_f32_16x16x32_bf16 v[92:95], v[224:227], v[212:215], v[92:95]
	v_mfma_f32_16x16x32_bf16 v[56:59], v[220:223], v[192:195], v[56:59]
	v_mfma_f32_16x16x32_bf16 v[60:63], v[228:231], v[192:195], v[60:63]
	v_mfma_f32_16x16x32_bf16 v[64:67], v[220:223], v[200:203], v[64:67]
	v_mfma_f32_16x16x32_bf16 v[72:75], v[228:231], v[200:203], v[72:75]
	s_barrier
	v_mfma_f32_16x16x32_bf16 v[76:79], v[220:223], v[208:211], v[76:79]
	v_mfma_f32_16x16x32_bf16 v[80:83], v[228:231], v[208:211], v[80:83]
	v_mfma_f32_16x16x32_bf16 v[88:91], v[220:223], v[232:235], v[88:91]
	v_mfma_f32_16x16x32_bf16 v[92:95], v[228:231], v[232:235], v[92:95]
	s_setprio 0
	s_branch .LBB0_634
